# residual phases: each meta row's split-K partials summed by all 8 waves of its workgroup (LDS combine in fixed order)
# speedup vs baseline: 1.0288x; 1.0058x over previous
; __device__ __forceinline__ int opaque_tid() { int t = threadIdx.x; asm volatile("" : "+v"(t)); return t; }
; __device__ __forceinline__ void phase_resid(const Params& p, const float* g, bool first, bool last, int nsplit) {
;     const int tid = opaque_tid(), lane = tid & 63, gw = (blockIdx.x * NTHREADS + tid) >> 6, nw = (gridDim.x * NTHREADS) >> 6;
;     float* h = (float*)(p.ws + WS_H); bf16_t* abf = (bf16_t*)(p.ws + WS_ABF);
;     const bf16_t* mix = (const bf16_t*)(p.ws + WS_MIX);
;     const float* part = (const float*)(p.ws + WS_PART);
;     f32x4 gv[8];
; #pragma unroll
;     for (int i = 0; i < 8; ++i) gv[i] = *(const f32x4*)(g + lane * 4 + 256 * i);
;     ...
;     if (gw < 16) {
;         const int row = PADR + gw;
;         f32x4 mv[8], hv[8];
; #pragma unroll
;         for (int i = 0; i < 8; ++i) { mv[i] = (f32x4){0.f, 0.f, 0.f, 0.f}; hv[i] = *(const f32x4*)(HROW(row) + lane * 4 + 256 * i); }
;         for (int sp = 0; sp < nsplit; ++sp) {
; #pragma unroll
;             for (int i = 0; i < 8; ++i) mv[i] += *(const f32x4*)(part + (size_t)(sp * 16 + gw) * DM + lane * 4 + 256 * i);
;         }
.LBB0_300:
	v_writelane_b32 v254, s49, 28
	v_writelane_b32 v254, s48, 29
	v_writelane_b32 v254, s45, 30
	v_writelane_b32 v254, s44, 31
	v_writelane_b32 v254, s43, 32
	v_writelane_b32 v254, s42, 33
	v_writelane_b32 v254, s37, 34
	v_writelane_b32 v254, s36, 35
	v_writelane_b32 v254, s33, 36
	v_writelane_b32 v254, s29, 37
	v_writelane_b32 v254, s22, 38
	s_ashr_i32 s91, s90, 31
	s_nop 0
	v_writelane_b32 v254, s23, 39
	v_writelane_b32 v254, s21, 40
	v_writelane_b32 v254, s20, 41
	v_writelane_b32 v254, s19, 42
	v_writelane_b32 v254, s18, 43
	v_writelane_b32 v254, s17, 44
	v_writelane_b32 v254, s16, 45
	v_writelane_b32 v254, s12, 46
	v_writelane_b32 v254, s11, 47
	v_writelane_b32 v254, s10, 48
	v_writelane_b32 v254, s9, 49
	v_writelane_b32 v254, s8, 50
	v_writelane_b32 v254, s7, 51
	v_writelane_b32 v254, s5, 52
	s_mul_i32 s5, s90, 0x6280000
	v_writelane_b32 v254, s4, 53
	s_mul_hi_i32 s4, s90, 0x6280000
	s_add_u32 s5, s34, s5
	v_writelane_b32 v254, s5, 54
	s_addc_u32 s4, s35, s4
	v_writelane_b32 v254, s4, 55
	v_writelane_b32 v254, s50, 56
	s_cmp_lt_i32 s50, 5
	s_mov_b64 s[4:5], -1
	v_writelane_b32 v254, s31, 57
	s_cbranch_scc1 .LBB0_763
	v_readlane_b32 s4, v254, 56
	s_cmp_lt_i32 s4, 7
	s_mov_b64 s[4:5], -1
	s_cbranch_scc1 .LBB0_382
	v_readlane_b32 s4, v254, 56
	s_cmp_gt_i32 s4, 7
	s_mov_b64 s[4:5], -1
	s_cbranch_scc0 .LBB0_350
	s_lshl_b32 s4, s90, 11
	s_ashr_i32 s5, s4, 31
	v_mov_b32_e32 v34, v210
	s_lshl_b64 s[4:5], s[4:5], 2
	s_add_u32 s4, s6, s4
	v_lshlrev_b32_e32 v0, 2, v34
	v_and_b32_e32 v116, 0xfc, v0
	s_addc_u32 s5, s3, s5
	v_lshlrev_b32_e32 v0, 2, v116
	v_lshl_add_u64 v[18:19], s[4:5], 0, v[0:1]
	v_add_co_u32_e32 v30, vcc, 0x1000, v18
	global_load_dwordx4 v[2:5], v0, s[4:5]
	global_load_dwordx4 v[6:9], v0, s[4:5] offset:1024
	global_load_dwordx4 v[10:13], v0, s[4:5] offset:2048
	global_load_dwordx4 v[14:17], v0, s[4:5] offset:3072
	v_addc_co_u32_e32 v31, vcc, 0, v19, vcc
	global_load_dwordx4 v[18:21], v[30:31], off
	global_load_dwordx4 v[22:25], v[30:31], off offset:1024
	global_load_dwordx4 v[26:29], v[30:31], off offset:2048
	s_nop 0
	global_load_dwordx4 v[30:33], v[30:31], off offset:3072
	s_sub_i32 s3, s31, 28
	s_cmp_lt_u32 s3, 9
	s_cselect_b64 s[4:5], -1, 0
	s_cmp_gt_u32 s3, 8
	v_readlane_b32 s3, v252, 5
	s_cselect_b64 s[8:9], -1, 0
	s_add_u32 s16, s34, 0x18a00000
	v_add_u32_e32 v35, s3, v34
	s_movk_i32 s3, 0x400
	s_addc_u32 s17, s35, 0
	v_lshrrev_b32_e32 v70, 6, v35
	s_cmp_lt_u32 s80, 16
	s_cbranch_scc0 .Lmh_skip_p8
	v_and_b32_e32 v36, 63, v34
	v_lshrrev_b32_e32 v40, 6, v34
	v_lshlrev_b32_e32 v36, 4, v36
	v_lshl_add_u32 v42, v40, 13, v36
	v_lshl_add_u32 v36, v40, 17, v36
	s_lshl_b32 s100, s80, 13
	v_add_u32_e32 v36, s100, v36
	v_mov_b32_e32 v37, 0
	v_lshl_add_u64 v[36:37], s[34:35], 0, v[36:37]
	v_add_co_u32_e32 v36, vcc, 0x415c8500, v36
	s_nop 1
	v_addc_co_u32_e32 v37, vcc, 0, v37, vcc
	v_add_co_u32_e32 v38, vcc, 0x1000, v36
	s_nop 1
	v_addc_co_u32_e32 v39, vcc, 0, v37, vcc
	v_readfirstlane_b32 s100, v40
	global_load_dwordx4 v[152:155], v[36:37], off
	global_load_dwordx4 v[156:159], v[36:37], off offset:1024
	global_load_dwordx4 v[160:163], v[36:37], off offset:2048
	global_load_dwordx4 v[164:167], v[36:37], off offset:3072
	global_load_dwordx4 v[168:171], v[38:39], off
	global_load_dwordx4 v[172:175], v[38:39], off offset:1024
	global_load_dwordx4 v[176:179], v[38:39], off offset:2048
	global_load_dwordx4 v[180:183], v[38:39], off offset:3072
	v_add_co_u32_e32 v36, vcc, 0x100000, v36
	s_nop 1
	v_addc_co_u32_e32 v37, vcc, 0, v37, vcc
	v_add_co_u32_e32 v38, vcc, 0x100000, v38
	s_nop 1
	v_addc_co_u32_e32 v39, vcc, 0, v39, vcc
	global_load_dwordx4 v[184:187], v[36:37], off
	global_load_dwordx4 v[188:191], v[36:37], off offset:1024
	global_load_dwordx4 v[192:195], v[36:37], off offset:2048
	global_load_dwordx4 v[196:199], v[36:37], off offset:3072
	global_load_dwordx4 v[200:203], v[38:39], off
	global_load_dwordx4 v[204:207], v[38:39], off offset:1024
	global_load_dwordx4 v[224:227], v[38:39], off offset:2048
	global_load_dwordx4 v[228:231], v[38:39], off offset:3072
	s_cmp_lt_u32 s100, 6
	s_cbranch_scc0 .Lmh_two_p8
	v_add_co_u32_e32 v36, vcc, 0x100000, v36
	s_nop 1
	v_addc_co_u32_e32 v37, vcc, 0, v37, vcc
	v_add_co_u32_e32 v38, vcc, 0x100000, v38
	s_nop 1
	v_addc_co_u32_e32 v39, vcc, 0, v39, vcc
	global_load_dwordx4 v[232:235], v[36:37], off
	global_load_dwordx4 v[236:239], v[36:37], off offset:1024
	global_load_dwordx4 v[240:243], v[36:37], off offset:2048
	global_load_dwordx4 v[244:247], v[36:37], off offset:3072
	global_load_dwordx4 v[44:47], v[38:39], off
	global_load_dwordx4 v[48:51], v[38:39], off offset:1024
	global_load_dwordx4 v[52:55], v[38:39], off offset:2048
	global_load_dwordx4 v[56:59], v[38:39], off offset:3072
	s_waitcnt vmcnt(23)
	v_mov_b64_e32 v[120:121], v[152:153]
	v_mov_b64_e32 v[122:123], v[154:155]
	s_waitcnt vmcnt(22)
	v_mov_b64_e32 v[124:125], v[156:157]
	v_mov_b64_e32 v[126:127], v[158:159]
	s_waitcnt vmcnt(21)
	v_mov_b64_e32 v[128:129], v[160:161]
	v_mov_b64_e32 v[130:131], v[162:163]
	s_waitcnt vmcnt(20)
	v_mov_b64_e32 v[132:133], v[164:165]
	v_mov_b64_e32 v[134:135], v[166:167]
	s_waitcnt vmcnt(19)
	v_mov_b64_e32 v[136:137], v[168:169]
	v_mov_b64_e32 v[138:139], v[170:171]
	s_waitcnt vmcnt(18)
	v_mov_b64_e32 v[140:141], v[172:173]
	v_mov_b64_e32 v[142:143], v[174:175]
	s_waitcnt vmcnt(17)
	v_mov_b64_e32 v[144:145], v[176:177]
	v_mov_b64_e32 v[146:147], v[178:179]
	s_waitcnt vmcnt(16)
	v_mov_b64_e32 v[148:149], v[180:181]
	v_mov_b64_e32 v[150:151], v[182:183]
	s_waitcnt vmcnt(15)
	v_pk_add_f32 v[120:121], v[120:121], v[184:185]
	v_pk_add_f32 v[122:123], v[122:123], v[186:187]
	s_waitcnt vmcnt(14)
; __device__ __forceinline__ void phase_resid(const Params& p, const float* g, bool first, bool last, int nsplit) {
;     ...
;     if (gw < 16) {
;         const int row = PADR + gw;
;         f32x4 mv[8], hv[8];
; #pragma unroll
;         for (int i = 0; i < 8; ++i) { mv[i] = (f32x4){0.f, 0.f, 0.f, 0.f}; hv[i] = *(const f32x4*)(HROW(row) + lane * 4 + 256 * i); }
;         for (int sp = 0; sp < nsplit; ++sp) {
; #pragma unroll
;             for (int i = 0; i < 8; ++i) mv[i] += *(const f32x4*)(part + (size_t)(sp * 16 + gw) * DM + lane * 4 + 256 * i);
;         }
	v_pk_add_f32 v[124:125], v[124:125], v[188:189]
	v_pk_add_f32 v[126:127], v[126:127], v[190:191]
	s_waitcnt vmcnt(13)
	v_pk_add_f32 v[128:129], v[128:129], v[192:193]
	v_pk_add_f32 v[130:131], v[130:131], v[194:195]
	s_waitcnt vmcnt(12)
	v_pk_add_f32 v[132:133], v[132:133], v[196:197]
	v_pk_add_f32 v[134:135], v[134:135], v[198:199]
	s_waitcnt vmcnt(11)
	v_pk_add_f32 v[136:137], v[136:137], v[200:201]
	v_pk_add_f32 v[138:139], v[138:139], v[202:203]
	s_waitcnt vmcnt(10)
	v_pk_add_f32 v[140:141], v[140:141], v[204:205]
	v_pk_add_f32 v[142:143], v[142:143], v[206:207]
	s_waitcnt vmcnt(9)
	v_pk_add_f32 v[144:145], v[144:145], v[224:225]
	v_pk_add_f32 v[146:147], v[146:147], v[226:227]
	s_waitcnt vmcnt(8)
	v_pk_add_f32 v[148:149], v[148:149], v[228:229]
	v_pk_add_f32 v[150:151], v[150:151], v[230:231]
	s_waitcnt vmcnt(7)
	v_pk_add_f32 v[120:121], v[120:121], v[232:233]
	v_pk_add_f32 v[122:123], v[122:123], v[234:235]
	s_waitcnt vmcnt(6)
	v_pk_add_f32 v[124:125], v[124:125], v[236:237]
	v_pk_add_f32 v[126:127], v[126:127], v[238:239]
	s_waitcnt vmcnt(5)
	v_pk_add_f32 v[128:129], v[128:129], v[240:241]
	v_pk_add_f32 v[130:131], v[130:131], v[242:243]
	s_waitcnt vmcnt(4)
	v_pk_add_f32 v[132:133], v[132:133], v[244:245]
	v_pk_add_f32 v[134:135], v[134:135], v[246:247]
	s_waitcnt vmcnt(3)
	v_pk_add_f32 v[136:137], v[136:137], v[44:45]
	v_pk_add_f32 v[138:139], v[138:139], v[46:47]
	s_waitcnt vmcnt(2)
	v_pk_add_f32 v[140:141], v[140:141], v[48:49]
	v_pk_add_f32 v[142:143], v[142:143], v[50:51]
	s_waitcnt vmcnt(1)
	v_pk_add_f32 v[144:145], v[144:145], v[52:53]
	v_pk_add_f32 v[146:147], v[146:147], v[54:55]
	s_waitcnt vmcnt(0)
	v_pk_add_f32 v[148:149], v[148:149], v[56:57]
	v_pk_add_f32 v[150:151], v[150:151], v[58:59]
	s_branch .Lmh_pub_p8
.Lmh_two_p8:
	s_waitcnt vmcnt(15)
	v_mov_b64_e32 v[120:121], v[152:153]
	v_mov_b64_e32 v[122:123], v[154:155]
	s_waitcnt vmcnt(14)
	v_mov_b64_e32 v[124:125], v[156:157]
	v_mov_b64_e32 v[126:127], v[158:159]
	s_waitcnt vmcnt(13)
	v_mov_b64_e32 v[128:129], v[160:161]
	v_mov_b64_e32 v[130:131], v[162:163]
	s_waitcnt vmcnt(12)
	v_mov_b64_e32 v[132:133], v[164:165]
	v_mov_b64_e32 v[134:135], v[166:167]
	s_waitcnt vmcnt(11)
	v_mov_b64_e32 v[136:137], v[168:169]
	v_mov_b64_e32 v[138:139], v[170:171]
	s_waitcnt vmcnt(10)
	v_mov_b64_e32 v[140:141], v[172:173]
	v_mov_b64_e32 v[142:143], v[174:175]
	s_waitcnt vmcnt(9)
	v_mov_b64_e32 v[144:145], v[176:177]
	v_mov_b64_e32 v[146:147], v[178:179]
	s_waitcnt vmcnt(8)
	v_mov_b64_e32 v[148:149], v[180:181]
	v_mov_b64_e32 v[150:151], v[182:183]
	s_waitcnt vmcnt(7)
	v_pk_add_f32 v[120:121], v[120:121], v[184:185]
	v_pk_add_f32 v[122:123], v[122:123], v[186:187]
	s_waitcnt vmcnt(6)
	v_pk_add_f32 v[124:125], v[124:125], v[188:189]
	v_pk_add_f32 v[126:127], v[126:127], v[190:191]
	s_waitcnt vmcnt(5)
	v_pk_add_f32 v[128:129], v[128:129], v[192:193]
	v_pk_add_f32 v[130:131], v[130:131], v[194:195]
	s_waitcnt vmcnt(4)
	v_pk_add_f32 v[132:133], v[132:133], v[196:197]
	v_pk_add_f32 v[134:135], v[134:135], v[198:199]
	s_waitcnt vmcnt(3)
	v_pk_add_f32 v[136:137], v[136:137], v[200:201]
	v_pk_add_f32 v[138:139], v[138:139], v[202:203]
	s_waitcnt vmcnt(2)
	v_pk_add_f32 v[140:141], v[140:141], v[204:205]
	v_pk_add_f32 v[142:143], v[142:143], v[206:207]
	s_waitcnt vmcnt(1)
	v_pk_add_f32 v[144:145], v[144:145], v[224:225]
	v_pk_add_f32 v[146:147], v[146:147], v[226:227]
	s_waitcnt vmcnt(0)
	v_pk_add_f32 v[148:149], v[148:149], v[228:229]
	v_pk_add_f32 v[150:151], v[150:151], v[230:231]
.Lmh_pub_p8:
	ds_write_b128 v42, v[120:123]
	ds_write_b128 v42, v[124:127] offset:1024
	ds_write_b128 v42, v[128:131] offset:2048
	ds_write_b128 v42, v[132:135] offset:3072
	ds_write_b128 v42, v[136:139] offset:4096
	ds_write_b128 v42, v[140:143] offset:5120
	ds_write_b128 v42, v[144:147] offset:6144
	ds_write_b128 v42, v[148:151] offset:7168
	s_waitcnt lgkmcnt(0)
	s_barrier
.Lmh_skip_p8:
	v_cmp_gt_u32_e32 vcc, 64, v34
	s_cmp_lt_u32 s80, 16
	s_cselect_b64 s[100:101], -1, 0
	s_and_b64 vcc, vcc, s[100:101]
	v_mov_b32_e32 v250, s80
	v_mov_b32_e32 v251, 0
	v_and_b32_e32 v148, 63, v34
	s_and_saveexec_b64 s[10:11], vcc
	v_readlane_b32 s12, v254, 5
	s_mov_b32 s3, 0x415c8000
	s_mov_b32 s20, 0x415c9000
	s_mov_b32 s21, 0x415ca000
	s_mov_b32 s22, 0x415e8000
	s_mov_b32 s23, 0x415e9000
	s_mov_b32 s25, 0x415ea000
	s_cbranch_execz .LBB0_308
; __device__ __forceinline__ void phase_resid(const Params& p, const float* g, bool first, bool last, int nsplit) {
;     ...
;     if (gw < 16) {
;         const int row = PADR + gw;
;         f32x4 mv[8], hv[8];
; #pragma unroll
;         for (int i = 0; i < 8; ++i) { mv[i] = (f32x4){0.f, 0.f, 0.f, 0.f}; hv[i] = *(const f32x4*)(HROW(row) + lane * 4 + 256 * i); }
;         for (int sp = 0; sp < nsplit; ++sp) {
; #pragma unroll
;             for (int i = 0; i < 8; ++i) mv[i] += *(const f32x4*)(part + (size_t)(sp * 16 + gw) * DM + lane * 4 + 256 * i);
;         }
	v_mov_b32_e32 v34, 0x78000
	v_lshl_or_b32 v66, v250, 11, v34
	v_mov_b32_e32 v67, v1
	v_lshl_add_u64 v[34:35], v[66:67], 2, s[16:17]
	v_lshl_add_u64 v[68:69], v[34:35], 0, v[0:1]
	v_add_co_u32_e32 v34, vcc, 0x1000, v68
	global_load_dwordx4 v[62:65], v[68:69], off
	global_load_dwordx4 v[58:61], v[68:69], off offset:1024
	global_load_dwordx4 v[54:57], v[68:69], off offset:2048
	global_load_dwordx4 v[50:53], v[68:69], off offset:3072
	v_addc_co_u32_e32 v35, vcc, 0, v69, vcc
	global_load_dwordx4 v[46:49], v[34:35], off
	global_load_dwordx4 v[42:45], v[34:35], off offset:1024
	global_load_dwordx4 v[38:41], v[34:35], off offset:2048
	s_nop 0
	global_load_dwordx4 v[34:37], v[34:35], off offset:3072
	s_mov_b64 s[6:7], 0x1000
	v_lshl_add_u64 v[78:79], v[68:69], 0, s[6:7]
	s_mov_b64 s[6:7], 0x1400
	v_mov_b32_e32 v71, v1
	v_lshl_add_u64 v[72:73], v[68:69], 0, s[6:7]
	s_mov_b64 s[6:7], 0x1800
	v_lshlrev_b64 v[80:81], 13, v[250:251]
	v_lshl_add_u64 v[74:75], v[68:69], 0, s[6:7]
	s_mov_b64 s[6:7], 0x1c00
	v_lshl_or_b32 v80, v148, 4, v80
	v_mov_b32_e32 v88, 0
	v_lshl_add_u64 v[76:77], v[68:69], 0, s[6:7]
	v_lshl_add_u64 v[96:97], s[34:35], 0, v[80:81]
	s_mov_b64 s[18:19], 0
	v_mov_b32_e32 v89, v88
	v_mov_b32_e32 v90, v88
	v_mov_b32_e32 v91, v88
	v_mov_b32_e32 v80, v88
	v_mov_b32_e32 v81, v88
	v_mov_b32_e32 v82, v88
	v_mov_b32_e32 v83, v88
	v_mov_b32_e32 v84, v88
	v_mov_b32_e32 v85, v88
	v_mov_b32_e32 v86, v88
	v_mov_b32_e32 v87, v88
	v_mov_b32_e32 v92, v88
	v_mov_b32_e32 v93, v88
	v_mov_b32_e32 v94, v88
	v_mov_b32_e32 v95, v88
	v_mov_b32_e32 v98, v88
	v_mov_b32_e32 v99, v88
	v_mov_b32_e32 v100, v88
	v_mov_b32_e32 v101, v88
	v_mov_b32_e32 v102, v88
	v_mov_b32_e32 v103, v88
	v_mov_b32_e32 v104, v88
	v_mov_b32_e32 v105, v88
	v_mov_b32_e32 v106, v88
	v_mov_b32_e32 v107, v88
	v_mov_b32_e32 v108, v88
	v_mov_b32_e32 v109, v88
	v_mov_b32_e32 v110, v88
	v_mov_b32_e32 v111, v88
	v_mov_b32_e32 v112, v88
	v_mov_b32_e32 v113, v88
	v_lshlrev_b32_e32 v117, 4, v148
	ds_read_b128 v[152:155], v117 offset:0
	ds_read_b128 v[156:159], v117 offset:1024
	ds_read_b128 v[160:163], v117 offset:2048
	ds_read_b128 v[164:167], v117 offset:3072
	ds_read_b128 v[168:171], v117 offset:4096
	ds_read_b128 v[172:175], v117 offset:5120
	ds_read_b128 v[176:179], v117 offset:6144
	ds_read_b128 v[180:183], v117 offset:7168
	s_waitcnt lgkmcnt(7)
	v_pk_add_f32 v[110:111], v[110:111], v[152:153]
	v_pk_add_f32 v[112:113], v[112:113], v[154:155]
	ds_read_b128 v[152:155], v117 offset:8192
	s_waitcnt lgkmcnt(7)
	v_pk_add_f32 v[106:107], v[106:107], v[156:157]
	v_pk_add_f32 v[108:109], v[108:109], v[158:159]
	ds_read_b128 v[156:159], v117 offset:9216
	s_waitcnt lgkmcnt(7)
	v_pk_add_f32 v[102:103], v[102:103], v[160:161]
	v_pk_add_f32 v[104:105], v[104:105], v[162:163]
	ds_read_b128 v[160:163], v117 offset:10240
	s_waitcnt lgkmcnt(7)
	v_pk_add_f32 v[98:99], v[98:99], v[164:165]
	v_pk_add_f32 v[100:101], v[100:101], v[166:167]
	ds_read_b128 v[164:167], v117 offset:11264
	s_waitcnt lgkmcnt(7)
	v_pk_add_f32 v[92:93], v[92:93], v[168:169]
	v_pk_add_f32 v[94:95], v[94:95], v[170:171]
	ds_read_b128 v[168:171], v117 offset:12288
	s_waitcnt lgkmcnt(7)
	v_pk_add_f32 v[84:85], v[84:85], v[172:173]
	v_pk_add_f32 v[86:87], v[86:87], v[174:175]
	ds_read_b128 v[172:175], v117 offset:13312
	s_waitcnt lgkmcnt(7)
	v_pk_add_f32 v[80:81], v[80:81], v[176:177]
	v_pk_add_f32 v[82:83], v[82:83], v[178:179]
	ds_read_b128 v[176:179], v117 offset:14336
	s_waitcnt lgkmcnt(7)
	v_pk_add_f32 v[88:89], v[88:89], v[180:181]
	v_pk_add_f32 v[90:91], v[90:91], v[182:183]
	ds_read_b128 v[180:183], v117 offset:15360
	s_waitcnt lgkmcnt(7)
	v_pk_add_f32 v[110:111], v[110:111], v[152:153]
	v_pk_add_f32 v[112:113], v[112:113], v[154:155]
	ds_read_b128 v[152:155], v117 offset:16384
	s_waitcnt lgkmcnt(7)
	v_pk_add_f32 v[106:107], v[106:107], v[156:157]
	v_pk_add_f32 v[108:109], v[108:109], v[158:159]
	ds_read_b128 v[156:159], v117 offset:17408
	s_waitcnt lgkmcnt(7)
	v_pk_add_f32 v[102:103], v[102:103], v[160:161]
	v_pk_add_f32 v[104:105], v[104:105], v[162:163]
	ds_read_b128 v[160:163], v117 offset:18432
	s_waitcnt lgkmcnt(7)
	v_pk_add_f32 v[98:99], v[98:99], v[164:165]
	v_pk_add_f32 v[100:101], v[100:101], v[166:167]
	ds_read_b128 v[164:167], v117 offset:19456
	s_waitcnt lgkmcnt(7)
	v_pk_add_f32 v[92:93], v[92:93], v[168:169]
	v_pk_add_f32 v[94:95], v[94:95], v[170:171]
	ds_read_b128 v[168:171], v117 offset:20480
	s_waitcnt lgkmcnt(7)
	v_pk_add_f32 v[84:85], v[84:85], v[172:173]
	v_pk_add_f32 v[86:87], v[86:87], v[174:175]
	ds_read_b128 v[172:175], v117 offset:21504
	s_waitcnt lgkmcnt(7)
	v_pk_add_f32 v[80:81], v[80:81], v[176:177]
	v_pk_add_f32 v[82:83], v[82:83], v[178:179]
	ds_read_b128 v[176:179], v117 offset:22528
	s_waitcnt lgkmcnt(7)
	v_pk_add_f32 v[88:89], v[88:89], v[180:181]
	v_pk_add_f32 v[90:91], v[90:91], v[182:183]
	ds_read_b128 v[180:183], v117 offset:23552
	s_waitcnt lgkmcnt(7)
	v_pk_add_f32 v[110:111], v[110:111], v[152:153]
	v_pk_add_f32 v[112:113], v[112:113], v[154:155]
	ds_read_b128 v[152:155], v117 offset:24576
	s_waitcnt lgkmcnt(7)
	v_pk_add_f32 v[106:107], v[106:107], v[156:157]
	v_pk_add_f32 v[108:109], v[108:109], v[158:159]
	ds_read_b128 v[156:159], v117 offset:25600
	s_waitcnt lgkmcnt(7)
	v_pk_add_f32 v[102:103], v[102:103], v[160:161]
	v_pk_add_f32 v[104:105], v[104:105], v[162:163]
	ds_read_b128 v[160:163], v117 offset:26624
	s_waitcnt lgkmcnt(7)
	v_pk_add_f32 v[98:99], v[98:99], v[164:165]
	v_pk_add_f32 v[100:101], v[100:101], v[166:167]
	ds_read_b128 v[164:167], v117 offset:27648
	s_waitcnt lgkmcnt(7)
	v_pk_add_f32 v[92:93], v[92:93], v[168:169]
	v_pk_add_f32 v[94:95], v[94:95], v[170:171]
	ds_read_b128 v[168:171], v117 offset:28672
	s_waitcnt lgkmcnt(7)
; __device__ __forceinline__ void phase_resid(const Params& p, const float* g, bool first, bool last, int nsplit) {
;     ...
;         for (int sp = 0; sp < nsplit; ++sp) {
; #pragma unroll
;             for (int i = 0; i < 8; ++i) mv[i] += *(const f32x4*)(part + (size_t)(sp * 16 + gw) * DM + lane * 4 + 256 * i);
;         }
	v_pk_add_f32 v[84:85], v[84:85], v[172:173]
	v_pk_add_f32 v[86:87], v[86:87], v[174:175]
	ds_read_b128 v[172:175], v117 offset:29696
	s_waitcnt lgkmcnt(7)
	v_pk_add_f32 v[80:81], v[80:81], v[176:177]
	v_pk_add_f32 v[82:83], v[82:83], v[178:179]
	ds_read_b128 v[176:179], v117 offset:30720
	s_waitcnt lgkmcnt(7)
	v_pk_add_f32 v[88:89], v[88:89], v[180:181]
	v_pk_add_f32 v[90:91], v[90:91], v[182:183]
	ds_read_b128 v[180:183], v117 offset:31744
	s_waitcnt lgkmcnt(7)
	v_pk_add_f32 v[110:111], v[110:111], v[152:153]
	v_pk_add_f32 v[112:113], v[112:113], v[154:155]
	ds_read_b128 v[152:155], v117 offset:32768
	s_waitcnt lgkmcnt(7)
	v_pk_add_f32 v[106:107], v[106:107], v[156:157]
	v_pk_add_f32 v[108:109], v[108:109], v[158:159]
	ds_read_b128 v[156:159], v117 offset:33792
	s_waitcnt lgkmcnt(7)
	v_pk_add_f32 v[102:103], v[102:103], v[160:161]
	v_pk_add_f32 v[104:105], v[104:105], v[162:163]
	ds_read_b128 v[160:163], v117 offset:34816
	s_waitcnt lgkmcnt(7)
	v_pk_add_f32 v[98:99], v[98:99], v[164:165]
	v_pk_add_f32 v[100:101], v[100:101], v[166:167]
	ds_read_b128 v[164:167], v117 offset:35840
	s_waitcnt lgkmcnt(7)
	v_pk_add_f32 v[92:93], v[92:93], v[168:169]
	v_pk_add_f32 v[94:95], v[94:95], v[170:171]
	ds_read_b128 v[168:171], v117 offset:36864
	s_waitcnt lgkmcnt(7)
	v_pk_add_f32 v[84:85], v[84:85], v[172:173]
	v_pk_add_f32 v[86:87], v[86:87], v[174:175]
	ds_read_b128 v[172:175], v117 offset:37888
	s_waitcnt lgkmcnt(7)
	v_pk_add_f32 v[80:81], v[80:81], v[176:177]
	v_pk_add_f32 v[82:83], v[82:83], v[178:179]
	ds_read_b128 v[176:179], v117 offset:38912
	s_waitcnt lgkmcnt(7)
	v_pk_add_f32 v[88:89], v[88:89], v[180:181]
	v_pk_add_f32 v[90:91], v[90:91], v[182:183]
	ds_read_b128 v[180:183], v117 offset:39936
	s_waitcnt lgkmcnt(7)
	v_pk_add_f32 v[110:111], v[110:111], v[152:153]
	v_pk_add_f32 v[112:113], v[112:113], v[154:155]
	ds_read_b128 v[152:155], v117 offset:40960
	s_waitcnt lgkmcnt(7)
	v_pk_add_f32 v[106:107], v[106:107], v[156:157]
	v_pk_add_f32 v[108:109], v[108:109], v[158:159]
	ds_read_b128 v[156:159], v117 offset:41984
	s_waitcnt lgkmcnt(7)
	v_pk_add_f32 v[102:103], v[102:103], v[160:161]
	v_pk_add_f32 v[104:105], v[104:105], v[162:163]
	ds_read_b128 v[160:163], v117 offset:43008
	s_waitcnt lgkmcnt(7)
	v_pk_add_f32 v[98:99], v[98:99], v[164:165]
	v_pk_add_f32 v[100:101], v[100:101], v[166:167]
	ds_read_b128 v[164:167], v117 offset:44032
	s_waitcnt lgkmcnt(7)
	v_pk_add_f32 v[92:93], v[92:93], v[168:169]
	v_pk_add_f32 v[94:95], v[94:95], v[170:171]
	ds_read_b128 v[168:171], v117 offset:45056
	s_waitcnt lgkmcnt(7)
	v_pk_add_f32 v[84:85], v[84:85], v[172:173]
	v_pk_add_f32 v[86:87], v[86:87], v[174:175]
	ds_read_b128 v[172:175], v117 offset:46080
	s_waitcnt lgkmcnt(7)
	v_pk_add_f32 v[80:81], v[80:81], v[176:177]
	v_pk_add_f32 v[82:83], v[82:83], v[178:179]
	ds_read_b128 v[176:179], v117 offset:47104
	s_waitcnt lgkmcnt(7)
	v_pk_add_f32 v[88:89], v[88:89], v[180:181]
	v_pk_add_f32 v[90:91], v[90:91], v[182:183]
	ds_read_b128 v[180:183], v117 offset:48128
	s_waitcnt lgkmcnt(7)
	v_pk_add_f32 v[110:111], v[110:111], v[152:153]
	v_pk_add_f32 v[112:113], v[112:113], v[154:155]
	ds_read_b128 v[152:155], v117 offset:49152
	s_waitcnt lgkmcnt(7)
	v_pk_add_f32 v[106:107], v[106:107], v[156:157]
	v_pk_add_f32 v[108:109], v[108:109], v[158:159]
	ds_read_b128 v[156:159], v117 offset:50176
	s_waitcnt lgkmcnt(7)
	v_pk_add_f32 v[102:103], v[102:103], v[160:161]
	v_pk_add_f32 v[104:105], v[104:105], v[162:163]
	ds_read_b128 v[160:163], v117 offset:51200
	s_waitcnt lgkmcnt(7)
	v_pk_add_f32 v[98:99], v[98:99], v[164:165]
	v_pk_add_f32 v[100:101], v[100:101], v[166:167]
	ds_read_b128 v[164:167], v117 offset:52224
	s_waitcnt lgkmcnt(7)
	v_pk_add_f32 v[92:93], v[92:93], v[168:169]
	v_pk_add_f32 v[94:95], v[94:95], v[170:171]
	ds_read_b128 v[168:171], v117 offset:53248
	s_waitcnt lgkmcnt(7)
	v_pk_add_f32 v[84:85], v[84:85], v[172:173]
	v_pk_add_f32 v[86:87], v[86:87], v[174:175]
	ds_read_b128 v[172:175], v117 offset:54272
	s_waitcnt lgkmcnt(7)
	v_pk_add_f32 v[80:81], v[80:81], v[176:177]
	v_pk_add_f32 v[82:83], v[82:83], v[178:179]
	ds_read_b128 v[176:179], v117 offset:55296
	s_waitcnt lgkmcnt(7)
	v_pk_add_f32 v[88:89], v[88:89], v[180:181]
	v_pk_add_f32 v[90:91], v[90:91], v[182:183]
	ds_read_b128 v[180:183], v117 offset:56320
	s_waitcnt lgkmcnt(7)
	v_pk_add_f32 v[110:111], v[110:111], v[152:153]
	v_pk_add_f32 v[112:113], v[112:113], v[154:155]
	ds_read_b128 v[152:155], v117 offset:57344
	s_waitcnt lgkmcnt(7)
	v_pk_add_f32 v[106:107], v[106:107], v[156:157]
	v_pk_add_f32 v[108:109], v[108:109], v[158:159]
	ds_read_b128 v[156:159], v117 offset:58368
	s_waitcnt lgkmcnt(7)
	v_pk_add_f32 v[102:103], v[102:103], v[160:161]
	v_pk_add_f32 v[104:105], v[104:105], v[162:163]
	ds_read_b128 v[160:163], v117 offset:59392
	s_waitcnt lgkmcnt(7)
	v_pk_add_f32 v[98:99], v[98:99], v[164:165]
	v_pk_add_f32 v[100:101], v[100:101], v[166:167]
	ds_read_b128 v[164:167], v117 offset:60416
	s_waitcnt lgkmcnt(7)
	v_pk_add_f32 v[92:93], v[92:93], v[168:169]
	v_pk_add_f32 v[94:95], v[94:95], v[170:171]
	ds_read_b128 v[168:171], v117 offset:61440
	s_waitcnt lgkmcnt(7)
	v_pk_add_f32 v[84:85], v[84:85], v[172:173]
	v_pk_add_f32 v[86:87], v[86:87], v[174:175]
	ds_read_b128 v[172:175], v117 offset:62464
	s_waitcnt lgkmcnt(7)
	v_pk_add_f32 v[80:81], v[80:81], v[176:177]
	v_pk_add_f32 v[82:83], v[82:83], v[178:179]
	ds_read_b128 v[176:179], v117 offset:63488
	s_waitcnt lgkmcnt(7)
	v_pk_add_f32 v[88:89], v[88:89], v[180:181]
	v_pk_add_f32 v[90:91], v[90:91], v[182:183]
	ds_read_b128 v[180:183], v117 offset:64512
	s_waitcnt lgkmcnt(7)
	v_pk_add_f32 v[110:111], v[110:111], v[152:153]
	v_pk_add_f32 v[112:113], v[112:113], v[154:155]
	s_waitcnt lgkmcnt(6)
	v_pk_add_f32 v[106:107], v[106:107], v[156:157]
	v_pk_add_f32 v[108:109], v[108:109], v[158:159]
	s_waitcnt lgkmcnt(5)
	v_pk_add_f32 v[102:103], v[102:103], v[160:161]
	v_pk_add_f32 v[104:105], v[104:105], v[162:163]
	s_waitcnt lgkmcnt(4)
	v_pk_add_f32 v[98:99], v[98:99], v[164:165]
	v_pk_add_f32 v[100:101], v[100:101], v[166:167]
	s_waitcnt lgkmcnt(3)
	v_pk_add_f32 v[92:93], v[92:93], v[168:169]
	v_pk_add_f32 v[94:95], v[94:95], v[170:171]
	s_waitcnt lgkmcnt(2)
	v_pk_add_f32 v[84:85], v[84:85], v[172:173]
	v_pk_add_f32 v[86:87], v[86:87], v[174:175]
	s_waitcnt lgkmcnt(1)
	v_pk_add_f32 v[80:81], v[80:81], v[176:177]
	v_pk_add_f32 v[82:83], v[82:83], v[178:179]
	s_waitcnt lgkmcnt(0)
	v_pk_add_f32 v[88:89], v[88:89], v[180:181]
	v_pk_add_f32 v[90:91], v[90:91], v[182:183]
	s_waitcnt vmcnt(0) lgkmcnt(0)
	s_mov_b32 s18, 0x2c0000
	v_mul_f32_e32 v67, v111, v111
	v_mul_f32_e32 v71, v107, v107
	v_fmac_f32_e32 v67, v110, v110
	v_fmac_f32_e32 v71, v106, v106
	v_fmac_f32_e32 v67, v112, v112
	v_fmac_f32_e32 v71, v108, v108
	v_fmac_f32_e32 v67, v113, v113
	v_fmac_f32_e32 v71, v109, v109
	v_add_f32_e32 v67, v67, v71
	v_mul_f32_e32 v71, v103, v103
	v_fmac_f32_e32 v71, v102, v102
	v_fmac_f32_e32 v71, v104, v104
	v_fmac_f32_e32 v71, v105, v105
	v_add_f32_e32 v67, v67, v71
	v_mul_f32_e32 v71, v99, v99
	v_mov_b32_e32 v114, v93
	v_mov_b32_e32 v115, v85
	v_fmac_f32_e32 v71, v98, v98
	v_mov_b32_e32 v96, v92
	v_mov_b32_e32 v97, v84
	v_pk_mul_f32 v[114:115], v[114:115], v[114:115]
	v_fmac_f32_e32 v71, v100, v100
	v_pk_fma_f32 v[96:97], v[96:97], v[96:97], v[114:115]
	v_mov_b32_e32 v114, v94
	v_mov_b32_e32 v115, v86
	v_fmac_f32_e32 v71, v101, v101
	v_pk_fma_f32 v[96:97], v[114:115], v[114:115], v[96:97]
	v_mov_b32_e32 v114, v95
	v_mov_b32_e32 v115, v87
	v_add_f32_e32 v67, v67, v71
	v_pk_fma_f32 v[96:97], v[114:115], v[114:115], v[96:97]
	v_mov_b32_e32 v114, v81
	v_add_f32_e32 v67, v67, v96
	v_mov_b32_e32 v115, v89
	v_add_f32_e32 v67, v67, v97
	v_mov_b32_e32 v96, v80
	v_mov_b32_e32 v97, v88
	v_pk_mul_f32 v[114:115], v[114:115], v[114:115]
	s_nop 0
	v_pk_fma_f32 v[96:97], v[96:97], v[96:97], v[114:115]
	v_mov_b32_e32 v114, v82
	v_mov_b32_e32 v115, v90
	v_pk_fma_f32 v[96:97], v[114:115], v[114:115], v[96:97]
	v_mov_b32_e32 v114, v83
	v_mov_b32_e32 v115, v91
	v_pk_fma_f32 v[96:97], v[114:115], v[114:115], v[96:97]
	s_nop 0
	v_add_f32_e32 v67, v67, v96
	v_add_f32_e32 v71, v67, v97
	v_and_b32_e32 v67, 64, v215
	v_add_u32_e32 v115, 64, v67
	v_xor_b32_e32 v67, 32, v215
	v_cmp_lt_i32_e32 vcc, v67, v115
	s_nop 1
	v_cndmask_b32_e32 v67, v215, v67, vcc
	v_lshlrev_b32_e32 v67, 2, v67
	ds_bpermute_b32 v96, v67, v71
	s_waitcnt lgkmcnt(0)
	v_add_f32_e32 v96, v71, v96
	v_xor_b32_e32 v71, 16, v215
	v_cmp_lt_i32_e32 vcc, v71, v115
	s_nop 1
	v_cndmask_b32_e32 v71, v215, v71, vcc
	v_lshlrev_b32_e32 v71, 2, v71
	ds_bpermute_b32 v97, v71, v96
	s_waitcnt lgkmcnt(0)
	v_add_f32_e32 v97, v96, v97
	v_xor_b32_e32 v96, 8, v215
	v_cmp_lt_i32_e32 vcc, v96, v115
	s_nop 1
	v_cndmask_b32_e32 v96, v215, v96, vcc
	v_lshlrev_b32_e32 v96, 2, v96
	ds_bpermute_b32 v114, v96, v97
	s_waitcnt lgkmcnt(0)
	v_add_f32_e32 v114, v97, v114
	v_xor_b32_e32 v97, 4, v215
	v_cmp_lt_i32_e32 vcc, v97, v115
	s_nop 1
	v_cndmask_b32_e32 v97, v215, v97, vcc
	v_lshlrev_b32_e32 v97, 2, v97
	ds_bpermute_b32 v117, v97, v114
	s_waitcnt lgkmcnt(0)
	v_add_f32_e32 v117, v114, v117
	v_xor_b32_e32 v114, 2, v215
	v_cmp_lt_i32_e32 vcc, v114, v115
	s_nop 1
	v_cndmask_b32_e32 v114, v215, v114, vcc
	v_lshlrev_b32_e32 v114, 2, v114
	ds_bpermute_b32 v118, v114, v117
	s_waitcnt lgkmcnt(0)
	v_add_f32_e32 v117, v117, v118
	v_xor_b32_e32 v118, 1, v215
	v_cmp_lt_i32_e32 vcc, v118, v115
	s_nop 1
	v_cndmask_b32_e32 v115, v215, v118, vcc
	v_lshlrev_b32_e32 v115, 2, v115
	ds_bpermute_b32 v118, v115, v117
	s_andn2_b64 vcc, exec, s[8:9]
	s_cbranch_vccnz .LBB0_308
	s_waitcnt lgkmcnt(0)
	v_add_f32_e32 v117, v117, v118
	v_fmamk_f32 v117, v117, 0x3a000000, v212
	s_mov_b32 s3, 0x800000
	v_mul_f32_e32 v118, 0x4b800000, v117
	v_cmp_gt_f32_e32 vcc, s3, v117
	v_lshlrev_b32_e32 v66, 1, v66
	s_mov_b64 s[6:7], 0x1cc00000
	v_cndmask_b32_e32 v117, v117, v118, vcc
	v_rsq_f32_e32 v117, v117
	s_nop 0
	v_mul_f32_e32 v118, 0x45800000, v117
	v_cndmask_b32_e32 v118, v117, v118, vcc
	v_pk_mul_f32 v[110:111], v[110:111], v[118:119] op_sel_hi:[1,0]
	v_pk_mul_f32 v[106:107], v[106:107], v[118:119] op_sel_hi:[1,0]
	v_pk_fma_f32 v[62:63], v[2:3], v[110:111], v[62:63]
	v_pk_fma_f32 v[58:59], v[6:7], v[106:107], v[58:59]
	v_pk_mul_f32 v[102:103], v[102:103], v[118:119] op_sel_hi:[1,0]
	v_pk_mul_f32 v[112:113], v[112:113], v[118:119] op_sel_hi:[1,0]
	v_pk_mul_f32 v[108:109], v[108:109], v[118:119] op_sel_hi:[1,0]
	v_mul_f32_e32 v106, v63, v63
	v_pk_fma_f32 v[54:55], v[10:11], v[102:103], v[54:55]
	v_mul_f32_e32 v102, v59, v59
	v_pk_mul_f32 v[98:99], v[98:99], v[118:119] op_sel_hi:[1,0]
	v_pk_mul_f32 v[92:93], v[92:93], v[118:119] op_sel_hi:[1,0]
	v_pk_mul_f32 v[84:85], v[84:85], v[118:119] op_sel_hi:[1,0]
	v_pk_fma_f32 v[64:65], v[4:5], v[112:113], v[64:65]
	v_pk_fma_f32 v[60:61], v[8:9], v[108:109], v[60:61]
	v_fmac_f32_e32 v106, v62, v62
	v_pk_mul_f32 v[104:105], v[104:105], v[118:119] op_sel_hi:[1,0]
	v_fmac_f32_e32 v102, v58, v58
	v_pk_fma_f32 v[50:51], v[14:15], v[98:99], v[50:51]
	v_mul_f32_e32 v98, v55, v55
	v_pk_fma_f32 v[46:47], v[18:19], v[92:93], v[46:47]
	v_pk_mul_f32 v[86:87], v[86:87], v[118:119] op_sel_hi:[1,0]
	v_pk_fma_f32 v[42:43], v[22:23], v[84:85], v[42:43]
	v_fmac_f32_e32 v106, v64, v64
	v_pk_fma_f32 v[56:57], v[12:13], v[104:105], v[56:57]
	v_fmac_f32_e32 v102, v60, v60
	v_pk_mul_f32 v[100:101], v[100:101], v[118:119] op_sel_hi:[1,0]
	v_fmac_f32_e32 v98, v54, v54
	v_pk_mul_f32 v[94:95], v[94:95], v[118:119] op_sel_hi:[1,0]
	v_mul_f32_e32 v92, v51, v51
	v_pk_fma_f32 v[44:45], v[24:25], v[86:87], v[44:45]
	v_mov_b32_e32 v86, v43
	v_mov_b32_e32 v87, v47
	v_fmac_f32_e32 v106, v65, v65
	v_fmac_f32_e32 v102, v61, v61
	v_pk_fma_f32 v[52:53], v[16:17], v[100:101], v[52:53]
	v_fmac_f32_e32 v98, v56, v56
	v_pk_fma_f32 v[48:49], v[20:21], v[94:95], v[48:49]
	v_fmac_f32_e32 v92, v50, v50
	v_pk_mul_f32 v[82:83], v[82:83], v[118:119] op_sel_hi:[1,0]
	v_mov_b32_e32 v84, v42
	v_mov_b32_e32 v85, v46
	v_pk_mul_f32 v[86:87], v[86:87], v[86:87]
	v_add_f32_e32 v102, v106, v102
	v_fmac_f32_e32 v98, v57, v57
	v_fmac_f32_e32 v92, v52, v52
	v_pk_mul_f32 v[80:81], v[80:81], v[118:119] op_sel_hi:[1,0]
	v_pk_fma_f32 v[40:41], v[28:29], v[82:83], v[40:41]
	v_mov_b32_e32 v82, v44
	v_mov_b32_e32 v83, v48
	v_pk_fma_f32 v[84:85], v[84:85], v[84:85], v[86:87]
	v_add_f32_e32 v98, v98, v102
	v_fmac_f32_e32 v92, v53, v53
	v_pk_fma_f32 v[38:39], v[26:27], v[80:81], v[38:39]
	v_mov_b32_e32 v80, v45
	v_mov_b32_e32 v81, v49
	v_pk_fma_f32 v[82:83], v[82:83], v[82:83], v[84:85]
	v_add_f32_e32 v92, v92, v98
	v_pk_fma_f32 v[80:81], v[80:81], v[80:81], v[82:83]
	v_pk_mul_f32 v[82:83], v[88:89], v[118:119] op_sel_hi:[1,0]
	v_add_f32_e32 v81, v81, v92
	v_pk_fma_f32 v[34:35], v[30:31], v[82:83], v[34:35]
	v_add_f32_e32 v92, v80, v81
	v_pk_mul_f32 v[80:81], v[90:91], v[118:119] op_sel_hi:[1,0]
	v_mov_b32_e32 v86, v35
	v_mov_b32_e32 v87, v39
	v_pk_fma_f32 v[36:37], v[32:33], v[80:81], v[36:37]
	v_mov_b32_e32 v84, v34
	v_mov_b32_e32 v85, v38
	v_pk_mul_f32 v[86:87], v[86:87], v[86:87]
	v_mov_b32_e32 v82, v36
	v_mov_b32_e32 v83, v40
	v_pk_fma_f32 v[84:85], v[84:85], v[84:85], v[86:87]
	v_mov_b32_e32 v80, v37
	v_mov_b32_e32 v81, v41
	v_pk_fma_f32 v[82:83], v[82:83], v[82:83], v[84:85]
	global_store_dwordx4 v[68:69], v[62:65], off
	v_pk_fma_f32 v[80:81], v[80:81], v[80:81], v[82:83]
	global_store_dwordx4 v[68:69], v[58:61], off offset:1024
	global_store_dwordx4 v[68:69], v[54:57], off offset:2048
	global_store_dwordx4 v[68:69], v[50:53], off offset:3072
	global_store_dwordx4 v[78:79], v[46:49], off
	v_add_f32_e32 v81, v81, v92
	v_add_f32_e32 v80, v80, v81
	ds_bpermute_b32 v67, v67, v80
	v_mov_b32_e32 v69, v1
	global_store_dwordx4 v[72:73], v[42:45], off
	global_store_dwordx4 v[74:75], v[38:41], off
	global_store_dwordx4 v[76:77], v[34:37], off
	s_waitcnt lgkmcnt(0)
	v_add_f32_e32 v67, v80, v67
	ds_bpermute_b32 v71, v71, v67
	s_waitcnt lgkmcnt(0)
	v_add_f32_e32 v67, v67, v71
	ds_bpermute_b32 v71, v96, v67
	s_waitcnt lgkmcnt(0)
	v_add_f32_e32 v67, v67, v71
	ds_bpermute_b32 v71, v97, v67
	s_waitcnt lgkmcnt(0)
	v_add_f32_e32 v67, v67, v71
	ds_bpermute_b32 v71, v114, v67
	s_waitcnt lgkmcnt(0)
	v_add_f32_e32 v67, v67, v71
	ds_bpermute_b32 v71, v115, v67
	s_waitcnt lgkmcnt(0)
	v_add_f32_e32 v67, v67, v71
	v_fmamk_f32 v67, v67, 0x3a000000, v212
	v_mul_f32_e32 v68, 0x4b800000, v67
	v_cmp_gt_f32_e32 vcc, s3, v67
	s_mov_b32 s3, 0x1cc00000
	s_nop 0
	v_cndmask_b32_e32 v67, v67, v68, vcc
	v_rsq_f32_e32 v67, v67
	s_nop 0
	v_mul_f32_e32 v68, 0x45800000, v67
	v_cndmask_b32_e32 v71, v67, v68, vcc
	v_mov_b32_e32 v67, v1
	v_lshl_add_u64 v[66:67], s[34:35], 0, v[66:67]
	v_lshlrev_b32_e32 v68, 1, v116
	v_mul_f32_e32 v62, v62, v71
	v_mul_f32_e32 v63, v63, v71
	v_lshl_add_u64 v[66:67], v[66:67], 0, v[68:69]
	v_cvt_pk_bf16_f32 v62, v62, v63
	v_mul_f32_e32 v63, v64, v71
	v_mul_f32_e32 v64, v65, v71
	v_cvt_pk_bf16_f32 v63, v63, v64
	v_add_co_u32_e32 v64, vcc, s3, v66
	v_mul_f32_e32 v58, v58, v71
	s_nop 0
	v_addc_co_u32_e32 v65, vcc, 0, v67, vcc
	v_mul_f32_e32 v59, v59, v71
	v_lshl_add_u64 v[68:69], v[66:67], 0, s[6:7]
	global_store_dwordx2 v[64:65], v[62:63], off
	v_cvt_pk_bf16_f32 v58, v58, v59
	v_mul_f32_e32 v59, v60, v71
	v_mul_f32_e32 v54, v54, v71
	v_mul_f32_e32 v55, v55, v71
	v_mul_f32_e32 v60, v61, v71
	v_cvt_pk_bf16_f32 v59, v59, v60
	global_store_dwordx2 v[68:69], v[58:59], off offset:512
	v_cvt_pk_bf16_f32 v54, v54, v55
	v_mul_f32_e32 v55, v56, v71
	v_mul_f32_e32 v50, v50, v71
	v_mul_f32_e32 v51, v51, v71
	v_mul_f32_e32 v56, v57, v71
	v_cvt_pk_bf16_f32 v55, v55, v56
	global_store_dwordx2 v[68:69], v[54:55], off offset:1024
	v_cvt_pk_bf16_f32 v50, v50, v51
	v_mul_f32_e32 v51, v52, v71
	v_mul_f32_e32 v46, v46, v71
	v_mul_f32_e32 v47, v47, v71
	v_mul_f32_e32 v52, v53, v71
	v_cvt_pk_bf16_f32 v51, v51, v52
	global_store_dwordx2 v[68:69], v[50:51], off offset:1536
	v_cvt_pk_bf16_f32 v46, v46, v47
	v_mul_f32_e32 v47, v48, v71
	v_mul_f32_e32 v42, v42, v71
	v_mul_f32_e32 v43, v43, v71
	v_mul_f32_e32 v48, v49, v71
	v_cvt_pk_bf16_f32 v47, v47, v48
	global_store_dwordx2 v[68:69], v[46:47], off offset:2048
	v_cvt_pk_bf16_f32 v42, v42, v43
	v_mul_f32_e32 v43, v44, v71
	v_mul_f32_e32 v38, v38, v71
	v_mul_f32_e32 v39, v39, v71
	v_mul_f32_e32 v44, v45, v71
	v_cvt_pk_bf16_f32 v43, v43, v44
	global_store_dwordx2 v[68:69], v[42:43], off offset:2560
	v_cvt_pk_bf16_f32 v38, v38, v39
	v_mul_f32_e32 v39, v40, v71
	v_mul_f32_e32 v34, v34, v71
	v_mul_f32_e32 v35, v35, v71
	v_mul_f32_e32 v40, v41, v71
	v_cvt_pk_bf16_f32 v39, v39, v40
	global_store_dwordx2 v[68:69], v[38:39], off offset:3072
	v_cvt_pk_bf16_f32 v34, v34, v35
	v_mul_f32_e32 v35, v36, v71
	v_mul_f32_e32 v36, v37, v71
	v_cvt_pk_bf16_f32 v35, v35, v36
	global_store_dwordx2 v[68:69], v[34:35], off offset:3584

; __device__ __forceinline__ int opaque_tid() { int t = threadIdx.x; asm volatile("" : "+v"(t)); return t; }
; __device__ __forceinline__ void phase_resid(const Params& p, const float* g, bool first, bool last, int nsplit) {
;     const int tid = opaque_tid(), lane = tid & 63, gw = (blockIdx.x * NTHREADS + tid) >> 6, nw = (gridDim.x * NTHREADS) >> 6;
;     float* h = (float*)(p.ws + WS_H); bf16_t* abf = (bf16_t*)(p.ws + WS_ABF);
;     const bf16_t* mix = (const bf16_t*)(p.ws + WS_MIX);
;     const float* part = (const float*)(p.ws + WS_PART);
;     f32x4 gv[8];
; #pragma unroll
;     for (int i = 0; i < 8; ++i) gv[i] = *(const f32x4*)(g + lane * 4 + 256 * i);
;     ...
;     if (gw < 16) {
;         const int row = PADR + gw;
;         f32x4 mv[8], hv[8];
; #pragma unroll
;         for (int i = 0; i < 8; ++i) { mv[i] = (f32x4){0.f, 0.f, 0.f, 0.f}; hv[i] = *(const f32x4*)(HROW(row) + lane * 4 + 256 * i); }
;         for (int sp = 0; sp < nsplit; ++sp) {
; #pragma unroll
;             for (int i = 0; i < 8; ++i) mv[i] += *(const f32x4*)(part + (size_t)(sp * 16 + gw) * DM + lane * 4 + 256 * i);
;         }
.LBB0_763:
	s_andn2_b64 vcc, exec, s[4:5]
	s_cbranch_vccnz .LBB0_1567
	v_readlane_b32 s0, v254, 56
	s_cmp_lt_i32 s0, 3
	s_mov_b64 s[0:1], -1
	s_cbranch_scc1 .LBB0_806
	v_readlane_b32 s0, v254, 56
	s_cmp_gt_i32 s0, 3
	s_mov_b64 s[0:1], -1
	s_cbranch_scc0 .LBB0_778
	s_lshl_b32 s0, s90, 11
	s_ashr_i32 s1, s0, 31
	v_mov_b32_e32 v0, v210
	s_lshl_b64 s[0:1], s[0:1], 2
	s_add_u32 s0, s46, s0
	s_waitcnt vmcnt(0)
	v_lshlrev_b32_e32 v2, 2, v0
	v_and_b32_e32 v110, 0xfc, v2
	s_addc_u32 s1, s13, s1
	v_lshlrev_b32_e32 v98, 2, v110
	v_mov_b32_e32 v99, v1
	v_lshl_add_u64 v[18:19], s[0:1], 0, v[98:99]
	v_add_co_u32_e32 v30, vcc, 0x1000, v18
	global_load_dwordx4 v[2:5], v98, s[0:1]
	global_load_dwordx4 v[6:9], v98, s[0:1] offset:1024
	global_load_dwordx4 v[10:13], v98, s[0:1] offset:2048
	global_load_dwordx4 v[14:17], v98, s[0:1] offset:3072
	v_addc_co_u32_e32 v31, vcc, 0, v19, vcc
	global_load_dwordx4 v[18:21], v[30:31], off
	global_load_dwordx4 v[22:25], v[30:31], off offset:1024
	global_load_dwordx4 v[26:29], v[30:31], off offset:2048
	s_nop 0
	global_load_dwordx4 v[30:33], v[30:31], off offset:3072
	s_add_i32 s0, s31, 7
	s_cmp_lt_u32 s0, 17
	v_readlane_b32 s2, v252, 5
	s_cselect_b64 s[0:1], -1, 0
	s_add_u32 s8, s34, 0x18a00000
	v_add_u32_e32 v34, s2, v0
	s_movk_i32 s2, 0x400
	s_addc_u32 s9, s35, 0
	v_lshrrev_b32_e32 v66, 6, v34
	s_cmp_lt_u32 s80, 16
	s_cbranch_scc0 .Lmh_skip_p4
	v_and_b32_e32 v36, 63, v0
	v_lshrrev_b32_e32 v40, 6, v0
	v_lshlrev_b32_e32 v36, 4, v36
	v_lshl_add_u32 v42, v40, 13, v36
	v_lshl_add_u32 v36, v40, 17, v36
	s_lshl_b32 s100, s80, 13
	v_add_u32_e32 v36, s100, v36
	v_mov_b32_e32 v37, 0
	v_lshl_add_u64 v[36:37], s[34:35], 0, v[36:37]
	v_add_co_u32_e32 v36, vcc, 0x415c8500, v36
	s_nop 1
	v_addc_co_u32_e32 v37, vcc, 0, v37, vcc
	v_add_co_u32_e32 v38, vcc, 0x1000, v36
	s_nop 1
	v_addc_co_u32_e32 v39, vcc, 0, v37, vcc
	v_readfirstlane_b32 s100, v40
	global_load_dwordx4 v[152:155], v[36:37], off
	global_load_dwordx4 v[156:159], v[36:37], off offset:1024
	global_load_dwordx4 v[160:163], v[36:37], off offset:2048
	global_load_dwordx4 v[164:167], v[36:37], off offset:3072
	global_load_dwordx4 v[168:171], v[38:39], off
	global_load_dwordx4 v[172:175], v[38:39], off offset:1024
	global_load_dwordx4 v[176:179], v[38:39], off offset:2048
	global_load_dwordx4 v[180:183], v[38:39], off offset:3072
	v_add_co_u32_e32 v36, vcc, 0x100000, v36
	s_nop 1
	v_addc_co_u32_e32 v37, vcc, 0, v37, vcc
	v_add_co_u32_e32 v38, vcc, 0x100000, v38
	s_nop 1
	v_addc_co_u32_e32 v39, vcc, 0, v39, vcc
	global_load_dwordx4 v[184:187], v[36:37], off
	global_load_dwordx4 v[188:191], v[36:37], off offset:1024
	global_load_dwordx4 v[192:195], v[36:37], off offset:2048
	global_load_dwordx4 v[196:199], v[36:37], off offset:3072
	global_load_dwordx4 v[200:203], v[38:39], off
	global_load_dwordx4 v[204:207], v[38:39], off offset:1024
	global_load_dwordx4 v[224:227], v[38:39], off offset:2048
	global_load_dwordx4 v[228:231], v[38:39], off offset:3072
	s_waitcnt vmcnt(15)
	v_mov_b64_e32 v[120:121], v[152:153]
	v_mov_b64_e32 v[122:123], v[154:155]
	s_waitcnt vmcnt(14)
	v_mov_b64_e32 v[124:125], v[156:157]
	v_mov_b64_e32 v[126:127], v[158:159]
	s_waitcnt vmcnt(13)
	v_mov_b64_e32 v[128:129], v[160:161]
	v_mov_b64_e32 v[130:131], v[162:163]
	s_waitcnt vmcnt(12)
	v_mov_b64_e32 v[132:133], v[164:165]
	v_mov_b64_e32 v[134:135], v[166:167]
	s_waitcnt vmcnt(11)
	v_mov_b64_e32 v[136:137], v[168:169]
	v_mov_b64_e32 v[138:139], v[170:171]
	s_waitcnt vmcnt(10)
	v_mov_b64_e32 v[140:141], v[172:173]
	v_mov_b64_e32 v[142:143], v[174:175]
	s_waitcnt vmcnt(9)
	v_mov_b64_e32 v[144:145], v[176:177]
	v_mov_b64_e32 v[146:147], v[178:179]
	s_waitcnt vmcnt(8)
	v_mov_b64_e32 v[148:149], v[180:181]
	v_mov_b64_e32 v[150:151], v[182:183]
	s_waitcnt vmcnt(7)
	v_pk_add_f32 v[120:121], v[120:121], v[184:185]
	v_pk_add_f32 v[122:123], v[122:123], v[186:187]
	s_waitcnt vmcnt(6)
	v_pk_add_f32 v[124:125], v[124:125], v[188:189]
	v_pk_add_f32 v[126:127], v[126:127], v[190:191]
	s_waitcnt vmcnt(5)
	v_pk_add_f32 v[128:129], v[128:129], v[192:193]
	v_pk_add_f32 v[130:131], v[130:131], v[194:195]
	s_waitcnt vmcnt(4)
	v_pk_add_f32 v[132:133], v[132:133], v[196:197]
	v_pk_add_f32 v[134:135], v[134:135], v[198:199]
	s_waitcnt vmcnt(3)
	v_pk_add_f32 v[136:137], v[136:137], v[200:201]
	v_pk_add_f32 v[138:139], v[138:139], v[202:203]
	s_waitcnt vmcnt(2)
	v_pk_add_f32 v[140:141], v[140:141], v[204:205]
	v_pk_add_f32 v[142:143], v[142:143], v[206:207]
	s_waitcnt vmcnt(1)
	v_pk_add_f32 v[144:145], v[144:145], v[224:225]
	v_pk_add_f32 v[146:147], v[146:147], v[226:227]
	s_waitcnt vmcnt(0)
	v_pk_add_f32 v[148:149], v[148:149], v[228:229]
	v_pk_add_f32 v[150:151], v[150:151], v[230:231]

; __device__ __forceinline__ void phase_resid(const Params& p, const float* g, bool first, bool last, int nsplit) {
;     ...
;     if (gw < 16) {
;         const int row = PADR + gw;
;         f32x4 mv[8], hv[8];
; #pragma unroll
;         for (int i = 0; i < 8; ++i) { mv[i] = (f32x4){0.f, 0.f, 0.f, 0.f}; hv[i] = *(const f32x4*)(HROW(row) + lane * 4 + 256 * i); }
;         for (int sp = 0; sp < nsplit; ++sp) {
; #pragma unroll
;             for (int i = 0; i < 8; ++i) mv[i] += *(const f32x4*)(part + (size_t)(sp * 16 + gw) * DM + lane * 4 + 256 * i);
;         }
.Lmh_skip_p4:
	v_cmp_gt_u32_e32 vcc, 64, v0
	s_cmp_lt_u32 s80, 16
	s_cselect_b64 s[100:101], -1, 0
	s_and_b64 vcc, vcc, s[100:101]
	v_mov_b32_e32 v250, s80
	v_mov_b32_e32 v251, 0
	v_and_b32_e32 v140, 63, v0
	s_and_saveexec_b64 s[4:5], vcc
	s_cbranch_execz .LBB0_770
	v_lshlrev_b32_e32 v34, 11, v250
	v_or_b32_e32 v0, 0x78000, v34
	v_mov_b32_e32 v35, v1
	v_lshl_add_u64 v[68:69], v[0:1], 2, s[8:9]
	v_lshl_add_u64 v[34:35], v[34:35], 2, s[40:41]
	v_cndmask_b32_e64 v35, v69, v35, s[0:1]
	v_cndmask_b32_e64 v34, v68, v34, s[0:1]
	v_lshl_add_u64 v[34:35], v[34:35], 0, v[98:99]
	s_movk_i32 s2, 0x1000
	global_load_dwordx4 v[62:65], v[34:35], off
	global_load_dwordx4 v[58:61], v[34:35], off offset:1024
	global_load_dwordx4 v[54:57], v[34:35], off offset:2048
	global_load_dwordx4 v[50:53], v[34:35], off offset:3072
	v_add_co_u32_e32 v34, vcc, s2, v34
	v_mov_b32_e32 v67, v1
	s_nop 0
	v_addc_co_u32_e32 v35, vcc, 0, v35, vcc
	global_load_dwordx4 v[46:49], v[34:35], off
	global_load_dwordx4 v[42:45], v[34:35], off offset:1024
	global_load_dwordx4 v[38:41], v[34:35], off offset:2048
	s_nop 0
	global_load_dwordx4 v[34:37], v[34:35], off offset:3072
	v_lshlrev_b64 v[70:71], 13, v[250:251]
	v_lshl_or_b32 v70, v140, 4, v70
	v_mov_b32_e32 v102, 0
	v_lshl_add_u64 v[70:71], s[34:35], 0, v[70:71]
	s_mov_b64 s[10:11], 0
	v_mov_b32_e32 v103, v102
	v_mov_b32_e32 v104, v102
	v_mov_b32_e32 v105, v102
	v_mov_b32_e32 v72, v102
	v_mov_b32_e32 v73, v102
	v_mov_b32_e32 v74, v102
	v_mov_b32_e32 v75, v102
	v_mov_b32_e32 v76, v102
	v_mov_b32_e32 v77, v102
	v_mov_b32_e32 v78, v102
	v_mov_b32_e32 v79, v102
	v_mov_b32_e32 v80, v102
	v_mov_b32_e32 v81, v102
	v_mov_b32_e32 v82, v102
	v_mov_b32_e32 v83, v102
	v_mov_b32_e32 v88, v102
	v_mov_b32_e32 v89, v102
	v_mov_b32_e32 v84, v102
	v_mov_b32_e32 v85, v102
	v_mov_b32_e32 v90, v102
	v_mov_b32_e32 v91, v102
	v_mov_b32_e32 v86, v102
	v_mov_b32_e32 v87, v102
	v_mov_b32_e32 v94, v102
	v_mov_b32_e32 v95, v102
	v_mov_b32_e32 v92, v102
	v_mov_b32_e32 v93, v102
	v_mov_b32_e32 v100, v102
	v_mov_b32_e32 v101, v102
	v_mov_b32_e32 v96, v102
	v_mov_b32_e32 v97, v102
	s_mov_b32 s3, 0x415c8000
	s_mov_b32 s6, 0x415c9000
	s_mov_b32 s7, 0x415ca000
	s_mov_b32 s12, 0x415e8000
	s_mov_b32 s13, 0x415e9000
	s_mov_b32 s14, 0x415ea000
	v_lshlrev_b32_e32 v117, 4, v140
	ds_read_b128 v[152:155], v117 offset:0
	ds_read_b128 v[156:159], v117 offset:1024
	ds_read_b128 v[160:163], v117 offset:2048
	ds_read_b128 v[164:167], v117 offset:3072
	ds_read_b128 v[168:171], v117 offset:4096
	ds_read_b128 v[172:175], v117 offset:5120
	ds_read_b128 v[176:179], v117 offset:6144
	ds_read_b128 v[180:183], v117 offset:7168
	s_waitcnt lgkmcnt(7)
	v_pk_add_f32 v[100:101], v[100:101], v[152:153]
	v_pk_add_f32 v[96:97], v[96:97], v[154:155]
	ds_read_b128 v[152:155], v117 offset:8192
	s_waitcnt lgkmcnt(7)
	v_pk_add_f32 v[94:95], v[94:95], v[156:157]
	v_pk_add_f32 v[92:93], v[92:93], v[158:159]
	ds_read_b128 v[156:159], v117 offset:9216
	s_waitcnt lgkmcnt(7)
	v_pk_add_f32 v[90:91], v[90:91], v[160:161]
	v_pk_add_f32 v[86:87], v[86:87], v[162:163]
	ds_read_b128 v[160:163], v117 offset:10240
	s_waitcnt lgkmcnt(7)
	v_pk_add_f32 v[88:89], v[88:89], v[164:165]
	v_pk_add_f32 v[84:85], v[84:85], v[166:167]
	ds_read_b128 v[164:167], v117 offset:11264
	s_waitcnt lgkmcnt(7)
	v_pk_add_f32 v[80:81], v[80:81], v[168:169]
	v_pk_add_f32 v[82:83], v[82:83], v[170:171]
	ds_read_b128 v[168:171], v117 offset:12288
	s_waitcnt lgkmcnt(7)
	v_pk_add_f32 v[76:77], v[76:77], v[172:173]
	v_pk_add_f32 v[78:79], v[78:79], v[174:175]
	ds_read_b128 v[172:175], v117 offset:13312
	s_waitcnt lgkmcnt(7)
	v_pk_add_f32 v[72:73], v[72:73], v[176:177]
	v_pk_add_f32 v[74:75], v[74:75], v[178:179]
	ds_read_b128 v[176:179], v117 offset:14336
	s_waitcnt lgkmcnt(7)
	v_pk_add_f32 v[102:103], v[102:103], v[180:181]
	v_pk_add_f32 v[104:105], v[104:105], v[182:183]
	ds_read_b128 v[180:183], v117 offset:15360
	s_waitcnt lgkmcnt(7)
	v_pk_add_f32 v[100:101], v[100:101], v[152:153]
	v_pk_add_f32 v[96:97], v[96:97], v[154:155]
	ds_read_b128 v[152:155], v117 offset:16384
	s_waitcnt lgkmcnt(7)
	v_pk_add_f32 v[94:95], v[94:95], v[156:157]
	v_pk_add_f32 v[92:93], v[92:93], v[158:159]
	ds_read_b128 v[156:159], v117 offset:17408
	s_waitcnt lgkmcnt(7)
	v_pk_add_f32 v[90:91], v[90:91], v[160:161]
	v_pk_add_f32 v[86:87], v[86:87], v[162:163]
	ds_read_b128 v[160:163], v117 offset:18432
	s_waitcnt lgkmcnt(7)
	v_pk_add_f32 v[88:89], v[88:89], v[164:165]
	v_pk_add_f32 v[84:85], v[84:85], v[166:167]
	ds_read_b128 v[164:167], v117 offset:19456
	s_waitcnt lgkmcnt(7)
	v_pk_add_f32 v[80:81], v[80:81], v[168:169]
	v_pk_add_f32 v[82:83], v[82:83], v[170:171]
	ds_read_b128 v[168:171], v117 offset:20480
	s_waitcnt lgkmcnt(7)
	v_pk_add_f32 v[76:77], v[76:77], v[172:173]
	v_pk_add_f32 v[78:79], v[78:79], v[174:175]
	ds_read_b128 v[172:175], v117 offset:21504
	s_waitcnt lgkmcnt(7)
	v_pk_add_f32 v[72:73], v[72:73], v[176:177]
	v_pk_add_f32 v[74:75], v[74:75], v[178:179]
	ds_read_b128 v[176:179], v117 offset:22528
	s_waitcnt lgkmcnt(7)
	v_pk_add_f32 v[102:103], v[102:103], v[180:181]
	v_pk_add_f32 v[104:105], v[104:105], v[182:183]
	ds_read_b128 v[180:183], v117 offset:23552
	s_waitcnt lgkmcnt(7)
	v_pk_add_f32 v[100:101], v[100:101], v[152:153]
	v_pk_add_f32 v[96:97], v[96:97], v[154:155]
	ds_read_b128 v[152:155], v117 offset:24576
	s_waitcnt lgkmcnt(7)
	v_pk_add_f32 v[94:95], v[94:95], v[156:157]
	v_pk_add_f32 v[92:93], v[92:93], v[158:159]
	ds_read_b128 v[156:159], v117 offset:25600
	s_waitcnt lgkmcnt(7)
	v_pk_add_f32 v[90:91], v[90:91], v[160:161]
	v_pk_add_f32 v[86:87], v[86:87], v[162:163]
	ds_read_b128 v[160:163], v117 offset:26624
	s_waitcnt lgkmcnt(7)
; __device__ __forceinline__ void phase_resid(const Params& p, const float* g, bool first, bool last, int nsplit) {
;     ...
;         for (int sp = 0; sp < nsplit; ++sp) {
; #pragma unroll
;             for (int i = 0; i < 8; ++i) mv[i] += *(const f32x4*)(part + (size_t)(sp * 16 + gw) * DM + lane * 4 + 256 * i);
;         }
	v_pk_add_f32 v[88:89], v[88:89], v[164:165]
	v_pk_add_f32 v[84:85], v[84:85], v[166:167]
	ds_read_b128 v[164:167], v117 offset:27648
	s_waitcnt lgkmcnt(7)
	v_pk_add_f32 v[80:81], v[80:81], v[168:169]
	v_pk_add_f32 v[82:83], v[82:83], v[170:171]
	ds_read_b128 v[168:171], v117 offset:28672
	s_waitcnt lgkmcnt(7)
	v_pk_add_f32 v[76:77], v[76:77], v[172:173]
	v_pk_add_f32 v[78:79], v[78:79], v[174:175]
	ds_read_b128 v[172:175], v117 offset:29696
	s_waitcnt lgkmcnt(7)
	v_pk_add_f32 v[72:73], v[72:73], v[176:177]
	v_pk_add_f32 v[74:75], v[74:75], v[178:179]
	ds_read_b128 v[176:179], v117 offset:30720
	s_waitcnt lgkmcnt(7)
	v_pk_add_f32 v[102:103], v[102:103], v[180:181]
	v_pk_add_f32 v[104:105], v[104:105], v[182:183]
	ds_read_b128 v[180:183], v117 offset:31744
	s_waitcnt lgkmcnt(7)
	v_pk_add_f32 v[100:101], v[100:101], v[152:153]
	v_pk_add_f32 v[96:97], v[96:97], v[154:155]
	ds_read_b128 v[152:155], v117 offset:32768
	s_waitcnt lgkmcnt(7)
	v_pk_add_f32 v[94:95], v[94:95], v[156:157]
	v_pk_add_f32 v[92:93], v[92:93], v[158:159]
	ds_read_b128 v[156:159], v117 offset:33792
	s_waitcnt lgkmcnt(7)
	v_pk_add_f32 v[90:91], v[90:91], v[160:161]
	v_pk_add_f32 v[86:87], v[86:87], v[162:163]
	ds_read_b128 v[160:163], v117 offset:34816
	s_waitcnt lgkmcnt(7)
	v_pk_add_f32 v[88:89], v[88:89], v[164:165]
	v_pk_add_f32 v[84:85], v[84:85], v[166:167]
	ds_read_b128 v[164:167], v117 offset:35840
	s_waitcnt lgkmcnt(7)
	v_pk_add_f32 v[80:81], v[80:81], v[168:169]
	v_pk_add_f32 v[82:83], v[82:83], v[170:171]
	ds_read_b128 v[168:171], v117 offset:36864
	s_waitcnt lgkmcnt(7)
	v_pk_add_f32 v[76:77], v[76:77], v[172:173]
	v_pk_add_f32 v[78:79], v[78:79], v[174:175]
	ds_read_b128 v[172:175], v117 offset:37888
	s_waitcnt lgkmcnt(7)
	v_pk_add_f32 v[72:73], v[72:73], v[176:177]
	v_pk_add_f32 v[74:75], v[74:75], v[178:179]
	ds_read_b128 v[176:179], v117 offset:38912
	s_waitcnt lgkmcnt(7)
	v_pk_add_f32 v[102:103], v[102:103], v[180:181]
	v_pk_add_f32 v[104:105], v[104:105], v[182:183]
	ds_read_b128 v[180:183], v117 offset:39936
	s_waitcnt lgkmcnt(7)
	v_pk_add_f32 v[100:101], v[100:101], v[152:153]
	v_pk_add_f32 v[96:97], v[96:97], v[154:155]
	ds_read_b128 v[152:155], v117 offset:40960
	s_waitcnt lgkmcnt(7)
	v_pk_add_f32 v[94:95], v[94:95], v[156:157]
	v_pk_add_f32 v[92:93], v[92:93], v[158:159]
	ds_read_b128 v[156:159], v117 offset:41984
	s_waitcnt lgkmcnt(7)
	v_pk_add_f32 v[90:91], v[90:91], v[160:161]
	v_pk_add_f32 v[86:87], v[86:87], v[162:163]
	ds_read_b128 v[160:163], v117 offset:43008
	s_waitcnt lgkmcnt(7)
	v_pk_add_f32 v[88:89], v[88:89], v[164:165]
	v_pk_add_f32 v[84:85], v[84:85], v[166:167]
	ds_read_b128 v[164:167], v117 offset:44032
	s_waitcnt lgkmcnt(7)
	v_pk_add_f32 v[80:81], v[80:81], v[168:169]
	v_pk_add_f32 v[82:83], v[82:83], v[170:171]
	ds_read_b128 v[168:171], v117 offset:45056
	s_waitcnt lgkmcnt(7)
	v_pk_add_f32 v[76:77], v[76:77], v[172:173]
	v_pk_add_f32 v[78:79], v[78:79], v[174:175]
	ds_read_b128 v[172:175], v117 offset:46080
	s_waitcnt lgkmcnt(7)
	v_pk_add_f32 v[72:73], v[72:73], v[176:177]
	v_pk_add_f32 v[74:75], v[74:75], v[178:179]
	ds_read_b128 v[176:179], v117 offset:47104
	s_waitcnt lgkmcnt(7)
	v_pk_add_f32 v[102:103], v[102:103], v[180:181]
	v_pk_add_f32 v[104:105], v[104:105], v[182:183]
	ds_read_b128 v[180:183], v117 offset:48128
	s_waitcnt lgkmcnt(7)
	v_pk_add_f32 v[100:101], v[100:101], v[152:153]
	v_pk_add_f32 v[96:97], v[96:97], v[154:155]
	ds_read_b128 v[152:155], v117 offset:49152
	s_waitcnt lgkmcnt(7)
	v_pk_add_f32 v[94:95], v[94:95], v[156:157]
	v_pk_add_f32 v[92:93], v[92:93], v[158:159]
	ds_read_b128 v[156:159], v117 offset:50176
	s_waitcnt lgkmcnt(7)
	v_pk_add_f32 v[90:91], v[90:91], v[160:161]
	v_pk_add_f32 v[86:87], v[86:87], v[162:163]
	ds_read_b128 v[160:163], v117 offset:51200
	s_waitcnt lgkmcnt(7)
	v_pk_add_f32 v[88:89], v[88:89], v[164:165]
	v_pk_add_f32 v[84:85], v[84:85], v[166:167]
	ds_read_b128 v[164:167], v117 offset:52224
	s_waitcnt lgkmcnt(7)
	v_pk_add_f32 v[80:81], v[80:81], v[168:169]
	v_pk_add_f32 v[82:83], v[82:83], v[170:171]
	ds_read_b128 v[168:171], v117 offset:53248
	s_waitcnt lgkmcnt(7)
	v_pk_add_f32 v[76:77], v[76:77], v[172:173]
	v_pk_add_f32 v[78:79], v[78:79], v[174:175]
	ds_read_b128 v[172:175], v117 offset:54272
	s_waitcnt lgkmcnt(7)
	v_pk_add_f32 v[72:73], v[72:73], v[176:177]
	v_pk_add_f32 v[74:75], v[74:75], v[178:179]
	ds_read_b128 v[176:179], v117 offset:55296
	s_waitcnt lgkmcnt(7)
	v_pk_add_f32 v[102:103], v[102:103], v[180:181]
	v_pk_add_f32 v[104:105], v[104:105], v[182:183]
	ds_read_b128 v[180:183], v117 offset:56320
	s_waitcnt lgkmcnt(7)
	v_pk_add_f32 v[100:101], v[100:101], v[152:153]
	v_pk_add_f32 v[96:97], v[96:97], v[154:155]
	ds_read_b128 v[152:155], v117 offset:57344
	s_waitcnt lgkmcnt(7)
	v_pk_add_f32 v[94:95], v[94:95], v[156:157]
	v_pk_add_f32 v[92:93], v[92:93], v[158:159]
	ds_read_b128 v[156:159], v117 offset:58368
	s_waitcnt lgkmcnt(7)
	v_pk_add_f32 v[90:91], v[90:91], v[160:161]
	v_pk_add_f32 v[86:87], v[86:87], v[162:163]
	ds_read_b128 v[160:163], v117 offset:59392
	s_waitcnt lgkmcnt(7)
	v_pk_add_f32 v[88:89], v[88:89], v[164:165]
	v_pk_add_f32 v[84:85], v[84:85], v[166:167]
	ds_read_b128 v[164:167], v117 offset:60416
	s_waitcnt lgkmcnt(7)
	v_pk_add_f32 v[80:81], v[80:81], v[168:169]
	v_pk_add_f32 v[82:83], v[82:83], v[170:171]
	ds_read_b128 v[168:171], v117 offset:61440
	s_waitcnt lgkmcnt(7)
	v_pk_add_f32 v[76:77], v[76:77], v[172:173]
	v_pk_add_f32 v[78:79], v[78:79], v[174:175]
	ds_read_b128 v[172:175], v117 offset:62464
	s_waitcnt lgkmcnt(7)
	v_pk_add_f32 v[72:73], v[72:73], v[176:177]
	v_pk_add_f32 v[74:75], v[74:75], v[178:179]
	ds_read_b128 v[176:179], v117 offset:63488
	s_waitcnt lgkmcnt(7)
	v_pk_add_f32 v[102:103], v[102:103], v[180:181]
	v_pk_add_f32 v[104:105], v[104:105], v[182:183]
	ds_read_b128 v[180:183], v117 offset:64512
	s_waitcnt lgkmcnt(7)
	v_pk_add_f32 v[100:101], v[100:101], v[152:153]
	v_pk_add_f32 v[96:97], v[96:97], v[154:155]
	s_waitcnt lgkmcnt(6)
	v_pk_add_f32 v[94:95], v[94:95], v[156:157]
	v_pk_add_f32 v[92:93], v[92:93], v[158:159]
	s_waitcnt lgkmcnt(5)
	v_pk_add_f32 v[90:91], v[90:91], v[160:161]
	v_pk_add_f32 v[86:87], v[86:87], v[162:163]
	s_waitcnt lgkmcnt(4)
	v_pk_add_f32 v[88:89], v[88:89], v[164:165]
	v_pk_add_f32 v[84:85], v[84:85], v[166:167]
	s_waitcnt lgkmcnt(3)
	v_pk_add_f32 v[80:81], v[80:81], v[168:169]
	v_pk_add_f32 v[82:83], v[82:83], v[170:171]
	s_waitcnt lgkmcnt(2)
	v_pk_add_f32 v[76:77], v[76:77], v[172:173]
	v_pk_add_f32 v[78:79], v[78:79], v[174:175]
	s_waitcnt lgkmcnt(1)
	v_pk_add_f32 v[72:73], v[72:73], v[176:177]
	v_pk_add_f32 v[74:75], v[74:75], v[178:179]
	s_waitcnt lgkmcnt(0)
	v_pk_add_f32 v[102:103], v[102:103], v[180:181]
	v_pk_add_f32 v[104:105], v[104:105], v[182:183]
	s_waitcnt vmcnt(0) lgkmcnt(0)
	s_mov_b32 s10, 0x200000
	v_mul_f32_e32 v67, v101, v101
	v_mul_f32_e32 v70, v95, v95
	v_fmac_f32_e32 v67, v100, v100
	v_fmac_f32_e32 v70, v94, v94
	v_fmac_f32_e32 v67, v96, v96
	v_fmac_f32_e32 v70, v92, v92
	v_fmac_f32_e32 v67, v97, v97
	v_fmac_f32_e32 v70, v93, v93
	v_add_f32_e32 v67, v67, v70
	v_mul_f32_e32 v70, v91, v91
	v_fmac_f32_e32 v70, v90, v90
	v_fmac_f32_e32 v70, v86, v86
	v_fmac_f32_e32 v70, v87, v87
	v_add_f32_e32 v67, v67, v70
	v_mul_f32_e32 v70, v89, v89
	v_fmac_f32_e32 v70, v88, v88
	v_fmac_f32_e32 v70, v84, v84
	v_fmac_f32_e32 v70, v85, v85
	v_mov_b32_e32 v106, v81
	v_mov_b32_e32 v107, v77
	v_add_f32_e32 v67, v67, v70
	v_mov_b32_e32 v70, v80
	v_mov_b32_e32 v71, v76
	v_pk_mul_f32 v[106:107], v[106:107], v[106:107]
	s_mov_b32 s3, 0x800000
	v_pk_fma_f32 v[70:71], v[70:71], v[70:71], v[106:107]
	v_mov_b32_e32 v106, v82
	v_mov_b32_e32 v107, v78
	v_pk_fma_f32 v[70:71], v[106:107], v[106:107], v[70:71]
	v_mov_b32_e32 v106, v83
	v_mov_b32_e32 v107, v79
	v_pk_fma_f32 v[70:71], v[106:107], v[106:107], v[70:71]
	v_mov_b32_e32 v106, v73
	v_add_f32_e32 v67, v67, v70
	v_mov_b32_e32 v107, v103
	v_add_f32_e32 v67, v67, v71
	v_mov_b32_e32 v70, v72
	v_mov_b32_e32 v71, v102
	v_pk_mul_f32 v[106:107], v[106:107], v[106:107]
	s_movk_i32 s2, 0x1000
	v_pk_fma_f32 v[70:71], v[70:71], v[70:71], v[106:107]
	v_mov_b32_e32 v106, v74
	v_mov_b32_e32 v107, v104
	v_pk_fma_f32 v[70:71], v[106:107], v[106:107], v[70:71]
	v_mov_b32_e32 v106, v75
	v_mov_b32_e32 v107, v105
	v_pk_fma_f32 v[70:71], v[106:107], v[106:107], v[70:71]
	v_lshlrev_b32_e32 v0, 1, v0
	v_add_f32_e32 v67, v67, v70
	v_and_b32_e32 v70, 64, v215
	v_add_f32_e32 v67, v67, v71
	v_add_u32_e32 v70, 64, v70
	v_xor_b32_e32 v71, 32, v215
	v_cmp_lt_i32_e32 vcc, v71, v70
	s_nop 1
	v_cndmask_b32_e32 v71, v215, v71, vcc
	v_lshlrev_b32_e32 v99, 2, v71
	ds_bpermute_b32 v71, v99, v67
	s_waitcnt lgkmcnt(0)
	v_add_f32_e32 v67, v67, v71
	v_xor_b32_e32 v71, 16, v215
	v_cmp_lt_i32_e32 vcc, v71, v70
	s_nop 1
	v_cndmask_b32_e32 v71, v215, v71, vcc
	v_lshlrev_b32_e32 v106, 2, v71
	ds_bpermute_b32 v71, v106, v67
	s_waitcnt lgkmcnt(0)
	v_add_f32_e32 v67, v67, v71
	v_xor_b32_e32 v71, 8, v215
	v_cmp_lt_i32_e32 vcc, v71, v70
	s_nop 1
	v_cndmask_b32_e32 v71, v215, v71, vcc
	v_lshlrev_b32_e32 v107, 2, v71
	ds_bpermute_b32 v71, v107, v67
	s_waitcnt lgkmcnt(0)
	v_add_f32_e32 v67, v67, v71
	v_xor_b32_e32 v71, 4, v215
	v_cmp_lt_i32_e32 vcc, v71, v70
	s_nop 1
	v_cndmask_b32_e32 v71, v215, v71, vcc
	v_lshlrev_b32_e32 v108, 2, v71
	ds_bpermute_b32 v71, v108, v67
	s_waitcnt lgkmcnt(0)
	v_add_f32_e32 v67, v67, v71
	v_xor_b32_e32 v71, 2, v215
	v_cmp_lt_i32_e32 vcc, v71, v70
	s_nop 1
	v_cndmask_b32_e32 v71, v215, v71, vcc
	v_lshlrev_b32_e32 v109, 2, v71
	ds_bpermute_b32 v71, v109, v67
	s_waitcnt lgkmcnt(0)
	v_add_f32_e32 v67, v67, v71
	v_xor_b32_e32 v71, 1, v215
	v_cmp_lt_i32_e32 vcc, v71, v70
	s_nop 1
	v_cndmask_b32_e32 v70, v215, v71, vcc
	v_lshlrev_b32_e32 v111, 2, v70
	ds_bpermute_b32 v70, v111, v67
	s_waitcnt lgkmcnt(0)
	v_add_f32_e32 v67, v67, v70
	v_fmamk_f32 v67, v67, 0x3a000000, v212
	v_mul_f32_e32 v70, 0x4b800000, v67
	v_cmp_gt_f32_e32 vcc, s3, v67
	s_nop 1
	v_cndmask_b32_e32 v67, v67, v70, vcc
	v_rsq_f32_e32 v67, v67
	s_nop 0
	v_mul_f32_e32 v70, 0x45800000, v67
	v_cndmask_b32_e32 v70, v67, v70, vcc
	v_pk_mul_f32 v[94:95], v[94:95], v[70:71] op_sel_hi:[1,0]
	v_pk_mul_f32 v[100:101], v[100:101], v[70:71] op_sel_hi:[1,0]
	v_pk_fma_f32 v[58:59], v[6:7], v[94:95], v[58:59]
	v_pk_mul_f32 v[96:97], v[96:97], v[70:71] op_sel_hi:[1,0]
	v_pk_mul_f32 v[92:93], v[92:93], v[70:71] op_sel_hi:[1,0]
	v_mul_f32_e32 v71, v59, v59
	v_pk_fma_f32 v[62:63], v[2:3], v[100:101], v[62:63]
	v_pk_fma_f32 v[60:61], v[8:9], v[92:93], v[60:61]
	v_fmac_f32_e32 v71, v58, v58
	v_mul_f32_e32 v67, v63, v63
	v_fmac_f32_e32 v71, v60, v60
	v_pk_fma_f32 v[64:65], v[4:5], v[96:97], v[64:65]
	v_fmac_f32_e32 v67, v62, v62
	v_fmac_f32_e32 v71, v61, v61
	v_fmac_f32_e32 v67, v64, v64
	v_pk_mul_f32 v[90:91], v[90:91], v[70:71] op_sel_hi:[1,0]
	v_fmac_f32_e32 v67, v65, v65
	v_pk_fma_f32 v[54:55], v[10:11], v[90:91], v[54:55]
	v_add_f32_e32 v67, v67, v71
	v_pk_mul_f32 v[86:87], v[86:87], v[70:71] op_sel_hi:[1,0]
	v_mul_f32_e32 v71, v55, v55
	v_pk_fma_f32 v[56:57], v[12:13], v[86:87], v[56:57]
	v_fmac_f32_e32 v71, v54, v54
	v_fmac_f32_e32 v71, v56, v56
	v_fmac_f32_e32 v71, v57, v57
	v_pk_mul_f32 v[86:87], v[88:89], v[70:71] op_sel_hi:[1,0]
	v_add_f32_e32 v67, v71, v67
	v_pk_fma_f32 v[50:51], v[14:15], v[86:87], v[50:51]
	v_pk_mul_f32 v[84:85], v[84:85], v[70:71] op_sel_hi:[1,0]
	v_mul_f32_e32 v71, v51, v51
	v_pk_fma_f32 v[52:53], v[16:17], v[84:85], v[52:53]
	v_fmac_f32_e32 v71, v50, v50
	v_fmac_f32_e32 v71, v52, v52
	v_fmac_f32_e32 v71, v53, v53
	v_pk_mul_f32 v[80:81], v[80:81], v[70:71] op_sel_hi:[1,0]
	v_pk_mul_f32 v[76:77], v[76:77], v[70:71] op_sel_hi:[1,0]
	v_pk_fma_f32 v[46:47], v[18:19], v[80:81], v[46:47]
	v_pk_mul_f32 v[78:79], v[78:79], v[70:71] op_sel_hi:[1,0]
	v_pk_fma_f32 v[42:43], v[22:23], v[76:77], v[42:43]
	v_pk_mul_f32 v[82:83], v[82:83], v[70:71] op_sel_hi:[1,0]
	v_pk_fma_f32 v[44:45], v[24:25], v[78:79], v[44:45]
	v_mov_b32_e32 v78, v43
	v_mov_b32_e32 v79, v47
	v_pk_fma_f32 v[48:49], v[20:21], v[82:83], v[48:49]
	v_mov_b32_e32 v76, v42
	v_mov_b32_e32 v77, v46
	v_pk_mul_f32 v[78:79], v[78:79], v[78:79]
	v_pk_mul_f32 v[72:73], v[72:73], v[70:71] op_sel_hi:[1,0]
	v_pk_fma_f32 v[76:77], v[76:77], v[76:77], v[78:79]
	v_mov_b32_e32 v78, v44
	v_mov_b32_e32 v79, v48
	v_pk_fma_f32 v[76:77], v[78:79], v[78:79], v[76:77]
	v_mov_b32_e32 v78, v45
	v_mov_b32_e32 v79, v49
	v_add_f32_e32 v67, v71, v67
	v_pk_fma_f32 v[76:77], v[78:79], v[78:79], v[76:77]
	v_pk_mul_f32 v[74:75], v[74:75], v[70:71] op_sel_hi:[1,0]
	v_pk_fma_f32 v[38:39], v[26:27], v[72:73], v[38:39]
	v_pk_mul_f32 v[72:73], v[104:105], v[70:71] op_sel_hi:[1,0]
	v_pk_mul_f32 v[70:71], v[102:103], v[70:71] op_sel_hi:[1,0]
	v_add_f32_e32 v67, v77, v67
	v_pk_fma_f32 v[34:35], v[30:31], v[70:71], v[34:35]
	v_add_f32_e32 v67, v76, v67
	v_mov_b32_e32 v76, v35
	v_mov_b32_e32 v77, v39
	v_pk_fma_f32 v[40:41], v[28:29], v[74:75], v[40:41]
	v_pk_fma_f32 v[36:37], v[32:33], v[72:73], v[36:37]
	v_mov_b32_e32 v74, v34
	v_mov_b32_e32 v75, v38
	v_pk_mul_f32 v[76:77], v[76:77], v[76:77]
	v_mov_b32_e32 v72, v36
	v_mov_b32_e32 v73, v40
	v_pk_fma_f32 v[74:75], v[74:75], v[74:75], v[76:77]
	v_mov_b32_e32 v70, v37
	v_mov_b32_e32 v71, v41
	v_pk_fma_f32 v[72:73], v[72:73], v[72:73], v[74:75]
	s_nop 0
	v_pk_fma_f32 v[70:71], v[70:71], v[70:71], v[72:73]
	s_nop 0
	v_add_f32_e32 v67, v71, v67
	v_add_f32_e32 v67, v70, v67
	ds_bpermute_b32 v70, v99, v67
	v_mov_b32_e32 v99, v1
	v_lshl_add_u64 v[68:69], v[68:69], 0, v[98:99]
	global_store_dwordx4 v[68:69], v[62:65], off
	global_store_dwordx4 v[68:69], v[58:61], off offset:1024
	global_store_dwordx4 v[68:69], v[54:57], off offset:2048
	global_store_dwordx4 v[68:69], v[50:53], off offset:3072
	v_add_co_u32_e32 v68, vcc, s2, v68
	s_waitcnt lgkmcnt(0)
	v_add_f32_e32 v67, v67, v70
	ds_bpermute_b32 v70, v106, v67
	v_addc_co_u32_e32 v69, vcc, 0, v69, vcc
	global_store_dwordx4 v[68:69], v[46:49], off
	global_store_dwordx4 v[68:69], v[42:45], off offset:1024
	global_store_dwordx4 v[68:69], v[38:41], off offset:2048
	global_store_dwordx4 v[68:69], v[34:37], off offset:3072
	s_waitcnt lgkmcnt(0)
	v_add_f32_e32 v67, v67, v70
	ds_bpermute_b32 v70, v107, v67
	s_waitcnt lgkmcnt(0)
	v_add_f32_e32 v67, v67, v70
	ds_bpermute_b32 v70, v108, v67
	s_waitcnt lgkmcnt(0)
	v_add_f32_e32 v67, v67, v70
	ds_bpermute_b32 v70, v109, v67
	s_waitcnt lgkmcnt(0)
	v_add_f32_e32 v67, v67, v70
	ds_bpermute_b32 v70, v111, v67
	s_waitcnt lgkmcnt(0)
	v_add_f32_e32 v67, v67, v70
	v_fmamk_f32 v67, v67, 0x3a000000, v212
	v_mul_f32_e32 v70, 0x4b800000, v67
	v_cmp_gt_f32_e32 vcc, s3, v67
	s_mov_b64 s[2:3], 0x1cc00000
	s_nop 0
	v_cndmask_b32_e32 v67, v67, v70, vcc
	v_rsq_f32_e32 v67, v67
	s_nop 0
	v_mul_f32_e32 v68, 0x45800000, v67
	v_cndmask_b32_e32 v67, v67, v68, vcc
	v_lshl_add_u64 v[68:69], s[34:35], 0, v[0:1]
	v_lshlrev_b32_e32 v0, 1, v110
	v_lshl_add_u64 v[68:69], v[68:69], 0, v[0:1]
	v_lshl_add_u64 v[70:71], v[68:69], 0, s[2:3]
	v_mul_f32_e32 v0, v62, v67
	v_mul_f32_e32 v62, v63, v67
	s_mov_b32 s2, 0x1cc00000
	v_cvt_pk_bf16_f32 v62, v0, v62
	v_mul_f32_e32 v0, v64, v67
	v_mul_f32_e32 v63, v65, v67
	v_add_co_u32_e32 v64, vcc, s2, v68
	v_cvt_pk_bf16_f32 v63, v0, v63
	v_mul_f32_e32 v0, v58, v67
	s_nop 0
	v_addc_co_u32_e32 v65, vcc, 0, v69, vcc
	v_mul_f32_e32 v58, v59, v67
	global_store_dwordx2 v[64:65], v[62:63], off
	v_cvt_pk_bf16_f32 v58, v0, v58
	v_mul_f32_e32 v0, v60, v67
	v_mul_f32_e32 v59, v61, v67
	v_cvt_pk_bf16_f32 v59, v0, v59
	v_mul_f32_e32 v0, v54, v67
	v_mul_f32_e32 v54, v55, v67
	global_store_dwordx2 v[70:71], v[58:59], off offset:512
	v_cvt_pk_bf16_f32 v54, v0, v54
	v_mul_f32_e32 v0, v56, v67
	v_mul_f32_e32 v55, v57, v67
	v_cvt_pk_bf16_f32 v55, v0, v55
	v_mul_f32_e32 v0, v50, v67
	v_mul_f32_e32 v50, v51, v67
	global_store_dwordx2 v[70:71], v[54:55], off offset:1024
	v_cvt_pk_bf16_f32 v50, v0, v50
	v_mul_f32_e32 v0, v52, v67
	v_mul_f32_e32 v51, v53, v67
	v_cvt_pk_bf16_f32 v51, v0, v51
	v_mul_f32_e32 v0, v46, v67
	v_mul_f32_e32 v46, v47, v67
	global_store_dwordx2 v[70:71], v[50:51], off offset:1536
	v_cvt_pk_bf16_f32 v46, v0, v46
	v_mul_f32_e32 v0, v48, v67
	v_mul_f32_e32 v47, v49, v67
	v_cvt_pk_bf16_f32 v47, v0, v47
	v_mul_f32_e32 v0, v42, v67
	v_mul_f32_e32 v42, v43, v67
	global_store_dwordx2 v[70:71], v[46:47], off offset:2048
	v_cvt_pk_bf16_f32 v42, v0, v42
	v_mul_f32_e32 v0, v44, v67
	v_mul_f32_e32 v43, v45, v67
	v_cvt_pk_bf16_f32 v43, v0, v43
	v_mul_f32_e32 v0, v38, v67
	v_mul_f32_e32 v38, v39, v67
	global_store_dwordx2 v[70:71], v[42:43], off offset:2560
	v_cvt_pk_bf16_f32 v38, v0, v38
	v_mul_f32_e32 v0, v40, v67
	v_mul_f32_e32 v39, v41, v67
	v_cvt_pk_bf16_f32 v39, v0, v39
	v_mul_f32_e32 v0, v34, v67
	v_mul_f32_e32 v34, v35, v67
	v_mul_f32_e32 v35, v37, v67
	global_store_dwordx2 v[70:71], v[38:39], off offset:3072
	v_cvt_pk_bf16_f32 v34, v0, v34
	v_mul_f32_e32 v0, v36, v67
	v_cvt_pk_bf16_f32 v35, v0, v35
	global_store_dwordx2 v[70:71], v[34:35], off offset:3584
